# residual / KVQ epilogues: the lane-xor-16 step of the row sum of squares uses v_permlane16_swap instead of a ds_swizzle round trip (32 sites, bit-identical)
# baseline (speedup 1.0000x reference)
.LBB0_703:
	s_lshl_b32 s40, s40, 8
	s_lshl_b32 s29, s42, 8
	s_ashr_i32 s41, s40, 31
	v_mbcnt_lo_u32_b32 v191, -1, 0
	v_mbcnt_hi_u32_b32 v191, -1, v191
	s_add_i32 s29, s29, s60
	v_ashrrev_i32_e32 v128, 2, v191
	s_or_b64 s[44:45], s[40:41], s[18:19]
	s_lshl_b64 s[40:41], s[40:41], 2
	v_and_or_b32 v198, v191, 15, s29
	v_and_b32_e32 v192, -4, v128
	s_add_u32 s40, s64, s40
	v_ashrrev_i32_e32 v193, 31, v192
	s_addc_u32 s41, s65, s41
	v_ashrrev_i32_e32 v199, 31, v198
	v_lshl_add_u64 v[200:201], v[192:193], 2, s[40:41]
	v_lshlrev_b64 v[128:129], 12, v[198:199]
	v_lshl_add_u64 v[128:129], v[200:201], 0, v[128:129]
	global_load_dwordx4 v[184:187], v[128:129], off
	global_load_dwordx4 v[216:219], v[128:129], off offset:64
	global_load_dwordx4 v[220:223], v[128:129], off offset:512
	global_load_dwordx4 v[224:227], v[128:129], off offset:576
	v_or_b32_e32 v212, 16, v198
	v_or_b32_e32 v208, 32, v198
	v_or_b32_e32 v204, 48, v198
	v_ashrrev_i32_e32 v213, 31, v212
	v_ashrrev_i32_e32 v209, 31, v208
	v_ashrrev_i32_e32 v205, 31, v204
	v_lshlrev_b64 v[128:129], 12, v[212:213]
	v_lshlrev_b64 v[130:131], 12, v[208:209]
	v_lshlrev_b64 v[132:133], 12, v[204:205]
	v_lshl_add_u64 v[128:129], v[200:201], 0, v[128:129]
	v_lshl_add_u64 v[130:131], v[200:201], 0, v[130:131]
	v_lshl_add_u64 v[228:229], v[200:201], 0, v[132:133]
	global_load_dwordx4 v[172:175], v[128:129], off
	global_load_dwordx4 v[168:171], v[128:129], off offset:64
	global_load_dwordx4 v[164:167], v[128:129], off offset:512
	global_load_dwordx4 v[160:163], v[128:129], off offset:576
	global_load_dwordx4 v[156:159], v[130:131], off
	global_load_dwordx4 v[152:155], v[130:131], off offset:64
	global_load_dwordx4 v[148:151], v[130:131], off offset:512
	global_load_dwordx4 v[144:147], v[130:131], off offset:576
	global_load_dwordx4 v[140:143], v[228:229], off
	global_load_dwordx4 v[136:139], v[228:229], off offset:64
	global_load_dwordx4 v[132:135], v[228:229], off offset:512
	s_nop 0
	global_load_dwordx4 v[128:131], v[228:229], off offset:576
	v_lshl_add_u64 v[192:193], s[44:45], 0, v[192:193]
	v_lshlrev_b64 v[228:229], 11, v[198:199]
	v_lshl_add_u64 v[230:231], v[192:193], 1, s[14:15]
	v_cmp_gt_u32_e32 vcc, 16, v191
	v_lshl_add_u64 v[228:229], v[230:231], 0, v[228:229]
	s_waitcnt vmcnt(0)
	v_pk_fma_f32 v[126:127], v[126:127], v[214:215], v[186:187] op_sel_hi:[1,0,1]
	v_pk_fma_f32 v[124:125], v[124:125], v[214:215], v[184:185] op_sel_hi:[1,0,1]
	v_pk_fma_f32 v[122:123], v[122:123], v[214:215], v[218:219] op_sel_hi:[1,0,1]
	v_pk_fma_f32 v[120:121], v[120:121], v[214:215], v[216:217] op_sel_hi:[1,0,1]
	v_pk_fma_f32 v[118:119], v[118:119], v[214:215], v[222:223] op_sel_hi:[1,0,1]
	v_pk_fma_f32 v[116:117], v[116:117], v[214:215], v[220:221] op_sel_hi:[1,0,1]
	v_pk_fma_f32 v[114:115], v[114:115], v[214:215], v[226:227] op_sel_hi:[1,0,1]
	v_pk_fma_f32 v[112:113], v[112:113], v[214:215], v[224:225] op_sel_hi:[1,0,1]
	v_cvt_pk_bf16_f32 v184, v124, v125
	v_cvt_pk_bf16_f32 v185, v126, v127
	v_mul_f32_e32 v125, v125, v125
	v_mul_f32_e32 v127, v127, v127
	v_cvt_pk_bf16_f32 v186, v120, v121
	v_cvt_pk_bf16_f32 v187, v122, v123
	v_mul_f32_e32 v121, v121, v121
	v_mul_f32_e32 v123, v123, v123
	v_cvt_pk_bf16_f32 v214, v116, v117
	v_cvt_pk_bf16_f32 v215, v118, v119
	v_mul_f32_e32 v117, v117, v117
	v_mul_f32_e32 v119, v119, v119
	v_cvt_pk_bf16_f32 v216, v112, v113
	v_cvt_pk_bf16_f32 v217, v114, v115
	v_mul_f32_e32 v113, v113, v113
	v_mul_f32_e32 v115, v115, v115
	v_fmac_f32_e32 v125, v124, v124
	v_fmac_f32_e32 v127, v126, v126
	v_fmac_f32_e32 v121, v120, v120
	v_fmac_f32_e32 v123, v122, v122
	v_fmac_f32_e32 v117, v116, v116
	v_fmac_f32_e32 v119, v118, v118
	v_fmac_f32_e32 v113, v112, v112
	v_fmac_f32_e32 v115, v114, v114
	v_add_f32_e32 v112, v125, v127
	v_add_f32_e32 v114, v121, v123
	v_add_f32_e32 v116, v117, v119
	v_add_f32_e32 v112, v112, v114
	v_add_f32_e32 v113, v113, v115
	v_add_f32_e32 v112, v112, v116
	v_add_f32_e32 v112, v112, v113
	v_mov_b32_e32 v113, v112
	global_store_dwordx2 v[228:229], v[184:185], off
	global_store_dwordx2 v[228:229], v[186:187], off offset:32
	global_store_dwordx2 v[228:229], v[214:215], off offset:256
	global_store_dwordx2 v[228:229], v[216:217], off offset:288
	s_waitcnt lgkmcnt(0)
	s_nop 1
	v_permlane16_swap_b32_e32 v112, v113
	v_add_f32_e32 v112, v112, v113
	v_mov_b32_e32 v113, v112
	s_nop 1
	v_permlane32_swap_b32_e32 v112, v113
	s_and_saveexec_b64 s[40:41], vcc
	s_cbranch_execz .LBB0_705
	v_lshl_add_u64 v[114:115], v[198:199], 2, s[16:17]
	v_add_f32_e32 v112, v112, v113
	global_atomic_add_f32 v[114:115], v112, off
.LBB0_705:
	s_or_b64 exec, exec, s[40:41]
	v_pk_fma_f32 v[108:109], v[108:109], v[210:211], v[172:173] op_sel_hi:[1,0,1]
	v_pk_fma_f32 v[110:111], v[110:111], v[210:211], v[174:175] op_sel_hi:[1,0,1]
	v_cvt_pk_bf16_f32 v112, v108, v109
	v_mul_f32_e32 v109, v109, v109
	v_fmac_f32_e32 v109, v108, v108
	v_mul_f32_e32 v108, v111, v111
	v_fmac_f32_e32 v108, v110, v110
	v_pk_fma_f32 v[104:105], v[104:105], v[210:211], v[168:169] op_sel_hi:[1,0,1]
	v_cvt_pk_bf16_f32 v113, v110, v111
	v_add_f32_e32 v110, v109, v108
	v_pk_fma_f32 v[106:107], v[106:107], v[210:211], v[170:171] op_sel_hi:[1,0,1]
	v_cvt_pk_bf16_f32 v108, v104, v105
	v_mul_f32_e32 v105, v105, v105
	v_fmac_f32_e32 v105, v104, v104
	v_mul_f32_e32 v104, v107, v107
	v_fmac_f32_e32 v104, v106, v106
	v_add_f32_e32 v104, v105, v104
	v_pk_fma_f32 v[100:101], v[100:101], v[210:211], v[164:165] op_sel_hi:[1,0,1]
	v_cvt_pk_bf16_f32 v109, v106, v107
	v_add_f32_e32 v106, v110, v104
	v_pk_fma_f32 v[102:103], v[102:103], v[210:211], v[166:167] op_sel_hi:[1,0,1]
	v_cvt_pk_bf16_f32 v104, v100, v101
	v_mul_f32_e32 v101, v101, v101
	v_fmac_f32_e32 v101, v100, v100
	v_mul_f32_e32 v100, v103, v103
	v_fmac_f32_e32 v100, v102, v102
	v_pk_fma_f32 v[98:99], v[98:99], v[210:211], v[162:163] op_sel_hi:[1,0,1]
	v_pk_fma_f32 v[96:97], v[96:97], v[210:211], v[160:161] op_sel_hi:[1,0,1]
	v_cvt_pk_bf16_f32 v105, v102, v103
	v_add_f32_e32 v100, v101, v100
	v_mul_f32_e32 v101, v97, v97
	v_mul_f32_e32 v102, v99, v99
	v_fmac_f32_e32 v101, v96, v96
	v_fmac_f32_e32 v102, v98, v98
	v_add_f32_e32 v100, v106, v100
	v_add_f32_e32 v101, v101, v102
	v_add_f32_e32 v100, v100, v101
	v_mov_b32_e32 v101, v100
	v_lshlrev_b64 v[114:115], 11, v[212:213]
	v_lshl_add_u64 v[114:115], s[14:15], 0, v[114:115]
	v_lshl_add_u64 v[114:115], v[192:193], 1, v[114:115]
	v_cvt_pk_bf16_f32 v96, v96, v97
	v_cvt_pk_bf16_f32 v97, v98, v99
	global_store_dwordx2 v[114:115], v[96:97], off offset:288
	s_waitcnt lgkmcnt(0)
	s_nop 1
	v_permlane16_swap_b32_e32 v100, v101
	v_add_f32_e32 v96, v100, v101
	v_mov_b32_e32 v97, v96
	s_nop 1
	v_permlane32_swap_b32_e32 v96, v97
	global_store_dwordx2 v[114:115], v[112:113], off
	global_store_dwordx2 v[114:115], v[108:109], off offset:32
	global_store_dwordx2 v[114:115], v[104:105], off offset:256
	s_and_saveexec_b64 s[40:41], vcc
	s_cbranch_execz .LBB0_707
	v_lshl_add_u64 v[98:99], v[212:213], 2, s[16:17]
	v_add_f32_e32 v96, v96, v97
	global_atomic_add_f32 v[98:99], v96, off
.LBB0_707:
	s_or_b64 exec, exec, s[40:41]
	v_pk_fma_f32 v[92:93], v[92:93], v[206:207], v[156:157] op_sel_hi:[1,0,1]
	v_pk_fma_f32 v[94:95], v[94:95], v[206:207], v[158:159] op_sel_hi:[1,0,1]
	v_cvt_pk_bf16_f32 v96, v92, v93
	v_mul_f32_e32 v93, v93, v93
	v_fmac_f32_e32 v93, v92, v92
	v_mul_f32_e32 v92, v95, v95
	v_fmac_f32_e32 v92, v94, v94
	v_pk_fma_f32 v[88:89], v[88:89], v[206:207], v[152:153] op_sel_hi:[1,0,1]
	v_cvt_pk_bf16_f32 v97, v94, v95
	v_add_f32_e32 v94, v93, v92
	v_pk_fma_f32 v[90:91], v[90:91], v[206:207], v[154:155] op_sel_hi:[1,0,1]
	v_cvt_pk_bf16_f32 v92, v88, v89
	v_mul_f32_e32 v89, v89, v89
	v_fmac_f32_e32 v89, v88, v88
	v_mul_f32_e32 v88, v91, v91
	v_fmac_f32_e32 v88, v90, v90
	v_add_f32_e32 v88, v89, v88
	v_pk_fma_f32 v[84:85], v[84:85], v[206:207], v[148:149] op_sel_hi:[1,0,1]
	v_cvt_pk_bf16_f32 v93, v90, v91
	v_add_f32_e32 v90, v94, v88
	v_pk_fma_f32 v[86:87], v[86:87], v[206:207], v[150:151] op_sel_hi:[1,0,1]
	v_cvt_pk_bf16_f32 v88, v84, v85
	v_mul_f32_e32 v85, v85, v85
	v_fmac_f32_e32 v85, v84, v84
	v_mul_f32_e32 v84, v87, v87
	v_fmac_f32_e32 v84, v86, v86
	v_pk_fma_f32 v[82:83], v[82:83], v[206:207], v[146:147] op_sel_hi:[1,0,1]
	v_pk_fma_f32 v[80:81], v[80:81], v[206:207], v[144:145] op_sel_hi:[1,0,1]
	v_cvt_pk_bf16_f32 v89, v86, v87
	v_add_f32_e32 v84, v85, v84
	v_mul_f32_e32 v85, v81, v81
	v_mul_f32_e32 v86, v83, v83
	v_fmac_f32_e32 v85, v80, v80
	v_fmac_f32_e32 v86, v82, v82
	v_add_f32_e32 v84, v90, v84
	v_add_f32_e32 v85, v85, v86
	v_add_f32_e32 v84, v84, v85
	v_mov_b32_e32 v85, v84
	v_lshlrev_b64 v[98:99], 11, v[208:209]
	v_lshl_add_u64 v[98:99], s[14:15], 0, v[98:99]
	v_lshl_add_u64 v[98:99], v[192:193], 1, v[98:99]
	v_cvt_pk_bf16_f32 v80, v80, v81
	v_cvt_pk_bf16_f32 v81, v82, v83
	global_store_dwordx2 v[98:99], v[80:81], off offset:288
	s_waitcnt lgkmcnt(0)
	s_nop 1
	v_permlane16_swap_b32_e32 v84, v85
	v_add_f32_e32 v80, v84, v85
	v_mov_b32_e32 v81, v80
	s_nop 1
	v_permlane32_swap_b32_e32 v80, v81
	global_store_dwordx2 v[98:99], v[96:97], off
	global_store_dwordx2 v[98:99], v[92:93], off offset:32
	global_store_dwordx2 v[98:99], v[88:89], off offset:256
	s_and_saveexec_b64 s[40:41], vcc
	s_cbranch_execz .LBB0_709
	v_lshl_add_u64 v[82:83], v[208:209], 2, s[16:17]
	v_add_f32_e32 v80, v80, v81
	global_atomic_add_f32 v[82:83], v80, off
.LBB0_709:
	s_or_b64 exec, exec, s[40:41]
	v_pk_fma_f32 v[76:77], v[76:77], v[202:203], v[140:141] op_sel_hi:[1,0,1]
	v_pk_fma_f32 v[78:79], v[78:79], v[202:203], v[142:143] op_sel_hi:[1,0,1]
	v_cvt_pk_bf16_f32 v80, v76, v77
	v_mul_f32_e32 v77, v77, v77
	v_fmac_f32_e32 v77, v76, v76
	v_mul_f32_e32 v76, v79, v79
	v_fmac_f32_e32 v76, v78, v78
	v_pk_fma_f32 v[72:73], v[72:73], v[202:203], v[136:137] op_sel_hi:[1,0,1]
	v_cvt_pk_bf16_f32 v81, v78, v79
	v_add_f32_e32 v78, v77, v76
	v_pk_fma_f32 v[74:75], v[74:75], v[202:203], v[138:139] op_sel_hi:[1,0,1]
	v_cvt_pk_bf16_f32 v76, v72, v73
	v_mul_f32_e32 v73, v73, v73
	v_fmac_f32_e32 v73, v72, v72
	v_mul_f32_e32 v72, v75, v75
	v_fmac_f32_e32 v72, v74, v74
	v_add_f32_e32 v72, v73, v72
	v_pk_fma_f32 v[68:69], v[68:69], v[202:203], v[132:133] op_sel_hi:[1,0,1]
	v_cvt_pk_bf16_f32 v77, v74, v75
	v_add_f32_e32 v74, v78, v72
	v_pk_fma_f32 v[70:71], v[70:71], v[202:203], v[134:135] op_sel_hi:[1,0,1]
	v_cvt_pk_bf16_f32 v72, v68, v69
	v_mul_f32_e32 v69, v69, v69
	v_fmac_f32_e32 v69, v68, v68
	v_mul_f32_e32 v68, v71, v71
	v_fmac_f32_e32 v68, v70, v70
	v_pk_fma_f32 v[66:67], v[66:67], v[202:203], v[130:131] op_sel_hi:[1,0,1]
	v_pk_fma_f32 v[64:65], v[64:65], v[202:203], v[128:129] op_sel_hi:[1,0,1]
	v_cvt_pk_bf16_f32 v73, v70, v71
	v_add_f32_e32 v68, v69, v68
	v_mul_f32_e32 v69, v65, v65
	v_mul_f32_e32 v70, v67, v67
	v_fmac_f32_e32 v69, v64, v64
	v_fmac_f32_e32 v70, v66, v66
	v_add_f32_e32 v68, v74, v68
	v_add_f32_e32 v69, v69, v70
	v_add_f32_e32 v68, v68, v69
	v_mov_b32_e32 v69, v68
	v_lshlrev_b64 v[82:83], 11, v[204:205]
	v_lshl_add_u64 v[82:83], s[14:15], 0, v[82:83]
	v_lshl_add_u64 v[82:83], v[192:193], 1, v[82:83]
	v_cvt_pk_bf16_f32 v64, v64, v65
	v_cvt_pk_bf16_f32 v65, v66, v67
	global_store_dwordx2 v[82:83], v[64:65], off offset:288
	s_waitcnt lgkmcnt(0)
	s_nop 1
	v_permlane16_swap_b32_e32 v68, v69
	v_add_f32_e32 v64, v68, v69
	v_mov_b32_e32 v65, v64
	s_nop 1
	v_permlane32_swap_b32_e32 v64, v65
	global_store_dwordx2 v[82:83], v[80:81], off
	global_store_dwordx2 v[82:83], v[76:77], off offset:32
	global_store_dwordx2 v[82:83], v[72:73], off offset:256
	s_and_saveexec_b64 s[40:41], vcc
	s_cbranch_execz .LBB0_711
	v_lshl_add_u64 v[66:67], v[204:205], 2, s[16:17]
	v_add_f32_e32 v64, v64, v65
	global_atomic_add_f32 v[66:67], v64, off
.LBB0_711:
	s_or_b64 exec, exec, s[40:41]
	v_add_u32_e32 v118, 0x80, v198
	v_ashrrev_i32_e32 v119, 31, v118
	v_lshlrev_b64 v[64:65], 12, v[118:119]
	v_lshl_add_u64 v[64:65], v[200:201], 0, v[64:65]
	global_load_dwordx4 v[120:123], v[64:65], off
	global_load_dwordx4 v[124:127], v[64:65], off offset:64
	global_load_dwordx4 v[128:131], v[64:65], off offset:512
	global_load_dwordx4 v[132:135], v[64:65], off offset:576
	v_add_u32_e32 v116, 0x90, v198
	v_add_u32_e32 v114, 0xa0, v198
	v_add_u32_e32 v112, 0xb0, v198
	v_ashrrev_i32_e32 v117, 31, v116
	v_ashrrev_i32_e32 v115, 31, v114
	v_ashrrev_i32_e32 v113, 31, v112
	v_lshlrev_b64 v[64:65], 12, v[116:117]
	v_lshlrev_b64 v[66:67], 12, v[114:115]
	v_lshlrev_b64 v[68:69], 12, v[112:113]
	v_lshl_add_u64 v[64:65], v[200:201], 0, v[64:65]
	v_lshl_add_u64 v[66:67], v[200:201], 0, v[66:67]
	v_lshl_add_u64 v[136:137], v[200:201], 0, v[68:69]
	global_load_dwordx4 v[108:111], v[64:65], off
	global_load_dwordx4 v[104:107], v[64:65], off offset:64
	global_load_dwordx4 v[100:103], v[64:65], off offset:512
	global_load_dwordx4 v[96:99], v[64:65], off offset:576
	global_load_dwordx4 v[92:95], v[66:67], off
	global_load_dwordx4 v[88:91], v[66:67], off offset:64
	global_load_dwordx4 v[84:87], v[66:67], off offset:512
	global_load_dwordx4 v[80:83], v[66:67], off offset:576
	global_load_dwordx4 v[76:79], v[136:137], off
	global_load_dwordx4 v[72:75], v[136:137], off offset:64
	global_load_dwordx4 v[68:71], v[136:137], off offset:512
	s_nop 0
	global_load_dwordx4 v[64:67], v[136:137], off offset:576
	v_lshlrev_b64 v[136:137], 11, v[118:119]
	v_lshl_add_u64 v[136:137], s[14:15], 0, v[136:137]
	v_lshl_add_u64 v[136:137], v[192:193], 1, v[136:137]
	s_waitcnt vmcnt(15)
	v_pk_fma_f32 v[62:63], v[62:63], v[196:197], v[122:123] op_sel_hi:[1,0,1]
	v_pk_fma_f32 v[60:61], v[60:61], v[196:197], v[120:121] op_sel_hi:[1,0,1]
	s_waitcnt vmcnt(14)
	v_pk_fma_f32 v[58:59], v[58:59], v[196:197], v[126:127] op_sel_hi:[1,0,1]
	v_pk_fma_f32 v[56:57], v[56:57], v[196:197], v[124:125] op_sel_hi:[1,0,1]
	s_waitcnt vmcnt(13)
	v_pk_fma_f32 v[54:55], v[54:55], v[196:197], v[130:131] op_sel_hi:[1,0,1]
	v_pk_fma_f32 v[52:53], v[52:53], v[196:197], v[128:129] op_sel_hi:[1,0,1]
	s_waitcnt vmcnt(12)
	v_pk_fma_f32 v[50:51], v[50:51], v[196:197], v[134:135] op_sel_hi:[1,0,1]
	v_pk_fma_f32 v[48:49], v[48:49], v[196:197], v[132:133] op_sel_hi:[1,0,1]
	v_cvt_pk_bf16_f32 v120, v60, v61
	v_cvt_pk_bf16_f32 v121, v62, v63
	v_mul_f32_e32 v61, v61, v61
	v_mul_f32_e32 v63, v63, v63
	v_cvt_pk_bf16_f32 v122, v56, v57
	v_cvt_pk_bf16_f32 v123, v58, v59
	v_mul_f32_e32 v57, v57, v57
	v_mul_f32_e32 v59, v59, v59
	v_cvt_pk_bf16_f32 v124, v52, v53
	v_cvt_pk_bf16_f32 v125, v54, v55
	v_mul_f32_e32 v53, v53, v53
	v_mul_f32_e32 v55, v55, v55
	v_cvt_pk_bf16_f32 v126, v48, v49
	v_cvt_pk_bf16_f32 v127, v50, v51
	v_mul_f32_e32 v49, v49, v49
	v_mul_f32_e32 v51, v51, v51
	v_fmac_f32_e32 v61, v60, v60
	v_fmac_f32_e32 v63, v62, v62
	v_fmac_f32_e32 v57, v56, v56
	v_fmac_f32_e32 v59, v58, v58
	v_fmac_f32_e32 v53, v52, v52
	v_fmac_f32_e32 v55, v54, v54
	v_fmac_f32_e32 v49, v48, v48
	v_fmac_f32_e32 v51, v50, v50
	v_add_f32_e32 v48, v61, v63
	v_add_f32_e32 v50, v57, v59
	v_add_f32_e32 v52, v53, v55
	v_add_f32_e32 v48, v48, v50
	v_add_f32_e32 v49, v49, v51
	v_add_f32_e32 v48, v48, v52
	v_add_f32_e32 v48, v48, v49
	v_mov_b32_e32 v49, v48
	global_store_dwordx2 v[136:137], v[120:121], off
	global_store_dwordx2 v[136:137], v[122:123], off offset:32
	global_store_dwordx2 v[136:137], v[124:125], off offset:256
	global_store_dwordx2 v[136:137], v[126:127], off offset:288
	s_waitcnt lgkmcnt(0)
	s_nop 1
	v_permlane16_swap_b32_e32 v48, v49
	v_add_f32_e32 v48, v48, v49
	v_mov_b32_e32 v49, v48
	s_nop 1
	v_permlane32_swap_b32_e32 v48, v49
	s_and_saveexec_b64 s[40:41], vcc
	s_cbranch_execz .LBB0_713
	v_lshl_add_u64 v[50:51], v[118:119], 2, s[16:17]
	v_add_f32_e32 v48, v48, v49
	global_atomic_add_f32 v[50:51], v48, off
.LBB0_713:
	s_or_b64 exec, exec, s[40:41]
	s_waitcnt vmcnt(15)
	v_pk_fma_f32 v[44:45], v[44:45], v[194:195], v[108:109] op_sel_hi:[1,0,1]
	v_pk_fma_f32 v[46:47], v[46:47], v[194:195], v[110:111] op_sel_hi:[1,0,1]
	v_cvt_pk_bf16_f32 v48, v44, v45
	v_mul_f32_e32 v45, v45, v45
	v_fmac_f32_e32 v45, v44, v44
	v_mul_f32_e32 v44, v47, v47
	v_fmac_f32_e32 v44, v46, v46
	s_waitcnt vmcnt(14)
	v_pk_fma_f32 v[40:41], v[40:41], v[194:195], v[104:105] op_sel_hi:[1,0,1]
	v_cvt_pk_bf16_f32 v49, v46, v47
	v_add_f32_e32 v46, v45, v44
	v_pk_fma_f32 v[42:43], v[42:43], v[194:195], v[106:107] op_sel_hi:[1,0,1]
	v_cvt_pk_bf16_f32 v44, v40, v41
	v_mul_f32_e32 v41, v41, v41
	v_fmac_f32_e32 v41, v40, v40
	v_mul_f32_e32 v40, v43, v43
	v_fmac_f32_e32 v40, v42, v42
	v_add_f32_e32 v40, v41, v40
	s_waitcnt vmcnt(13)
	v_pk_fma_f32 v[36:37], v[36:37], v[194:195], v[100:101] op_sel_hi:[1,0,1]
	v_cvt_pk_bf16_f32 v45, v42, v43
	v_add_f32_e32 v42, v46, v40
	v_pk_fma_f32 v[38:39], v[38:39], v[194:195], v[102:103] op_sel_hi:[1,0,1]
	v_cvt_pk_bf16_f32 v40, v36, v37
	v_mul_f32_e32 v37, v37, v37
	v_fmac_f32_e32 v37, v36, v36
	v_mul_f32_e32 v36, v39, v39
	v_fmac_f32_e32 v36, v38, v38
	s_waitcnt vmcnt(12)
	v_pk_fma_f32 v[34:35], v[34:35], v[194:195], v[98:99] op_sel_hi:[1,0,1]
	v_pk_fma_f32 v[32:33], v[32:33], v[194:195], v[96:97] op_sel_hi:[1,0,1]
	v_cvt_pk_bf16_f32 v41, v38, v39
	v_add_f32_e32 v36, v37, v36
	v_mul_f32_e32 v37, v33, v33
	v_mul_f32_e32 v38, v35, v35
	v_fmac_f32_e32 v37, v32, v32
	v_fmac_f32_e32 v38, v34, v34
	v_add_f32_e32 v36, v42, v36
	v_add_f32_e32 v37, v37, v38
	v_add_f32_e32 v36, v36, v37
	v_mov_b32_e32 v37, v36
	v_lshlrev_b64 v[50:51], 11, v[116:117]
	v_lshl_add_u64 v[50:51], s[14:15], 0, v[50:51]
	v_lshl_add_u64 v[50:51], v[192:193], 1, v[50:51]
	v_cvt_pk_bf16_f32 v32, v32, v33
	v_cvt_pk_bf16_f32 v33, v34, v35
	global_store_dwordx2 v[50:51], v[32:33], off offset:288
	s_waitcnt lgkmcnt(0)
	s_nop 1
	v_permlane16_swap_b32_e32 v36, v37
	v_add_f32_e32 v32, v36, v37
	v_mov_b32_e32 v33, v32
	s_nop 1
	v_permlane32_swap_b32_e32 v32, v33
	global_store_dwordx2 v[50:51], v[48:49], off
	global_store_dwordx2 v[50:51], v[44:45], off offset:32
	global_store_dwordx2 v[50:51], v[40:41], off offset:256
	s_and_saveexec_b64 s[40:41], vcc
	s_cbranch_execz .LBB0_715
	v_lshl_add_u64 v[34:35], v[116:117], 2, s[16:17]
	v_add_f32_e32 v32, v32, v33
	global_atomic_add_f32 v[34:35], v32, off
.LBB0_715:
	s_or_b64 exec, exec, s[40:41]
	s_waitcnt vmcnt(15)
	v_pk_fma_f32 v[28:29], v[28:29], v[190:191], v[92:93] op_sel_hi:[1,0,1]
	v_pk_fma_f32 v[30:31], v[30:31], v[190:191], v[94:95] op_sel_hi:[1,0,1]
	v_cvt_pk_bf16_f32 v32, v28, v29
	v_mul_f32_e32 v29, v29, v29
	v_fmac_f32_e32 v29, v28, v28
	v_mul_f32_e32 v28, v31, v31
	v_fmac_f32_e32 v28, v30, v30
	s_waitcnt vmcnt(14)
	v_pk_fma_f32 v[24:25], v[24:25], v[190:191], v[88:89] op_sel_hi:[1,0,1]
	v_cvt_pk_bf16_f32 v33, v30, v31
	v_add_f32_e32 v30, v29, v28
	v_pk_fma_f32 v[26:27], v[26:27], v[190:191], v[90:91] op_sel_hi:[1,0,1]
	v_cvt_pk_bf16_f32 v28, v24, v25
	v_mul_f32_e32 v25, v25, v25
	v_fmac_f32_e32 v25, v24, v24
	v_mul_f32_e32 v24, v27, v27
	v_fmac_f32_e32 v24, v26, v26
	v_add_f32_e32 v24, v25, v24
	s_waitcnt vmcnt(13)
	v_pk_fma_f32 v[20:21], v[20:21], v[190:191], v[84:85] op_sel_hi:[1,0,1]
	v_cvt_pk_bf16_f32 v29, v26, v27
	v_add_f32_e32 v26, v30, v24
	v_pk_fma_f32 v[22:23], v[22:23], v[190:191], v[86:87] op_sel_hi:[1,0,1]
	v_cvt_pk_bf16_f32 v24, v20, v21
	v_mul_f32_e32 v21, v21, v21
	v_fmac_f32_e32 v21, v20, v20
	v_mul_f32_e32 v20, v23, v23
	v_fmac_f32_e32 v20, v22, v22
	s_waitcnt vmcnt(12)
	v_pk_fma_f32 v[18:19], v[18:19], v[190:191], v[82:83] op_sel_hi:[1,0,1]
	v_pk_fma_f32 v[16:17], v[16:17], v[190:191], v[80:81] op_sel_hi:[1,0,1]
	v_cvt_pk_bf16_f32 v25, v22, v23
	v_add_f32_e32 v20, v21, v20
	v_mul_f32_e32 v21, v17, v17
	v_mul_f32_e32 v22, v19, v19
	v_fmac_f32_e32 v21, v16, v16
	v_fmac_f32_e32 v22, v18, v18
	v_add_f32_e32 v20, v26, v20
	v_add_f32_e32 v21, v21, v22
	v_add_f32_e32 v20, v20, v21
	v_mov_b32_e32 v21, v20
	v_lshlrev_b64 v[34:35], 11, v[114:115]
	v_lshl_add_u64 v[34:35], s[14:15], 0, v[34:35]
	v_lshl_add_u64 v[34:35], v[192:193], 1, v[34:35]
	v_cvt_pk_bf16_f32 v16, v16, v17
	v_cvt_pk_bf16_f32 v17, v18, v19
	global_store_dwordx2 v[34:35], v[16:17], off offset:288
	s_waitcnt lgkmcnt(0)
	s_nop 1
	v_permlane16_swap_b32_e32 v20, v21
	v_add_f32_e32 v16, v20, v21
	v_mov_b32_e32 v17, v16
	s_nop 1
	v_permlane32_swap_b32_e32 v16, v17
	global_store_dwordx2 v[34:35], v[32:33], off
	global_store_dwordx2 v[34:35], v[28:29], off offset:32
	global_store_dwordx2 v[34:35], v[24:25], off offset:256
	s_and_saveexec_b64 s[40:41], vcc
	s_cbranch_execz .LBB0_717
	v_lshl_add_u64 v[18:19], v[114:115], 2, s[16:17]
	v_add_f32_e32 v16, v16, v17
	global_atomic_add_f32 v[18:19], v16, off
.LBB0_717:
	s_or_b64 exec, exec, s[40:41]
	s_waitcnt vmcnt(15)
	v_pk_fma_f32 v[12:13], v[12:13], v[188:189], v[76:77] op_sel_hi:[1,0,1]
	v_pk_fma_f32 v[14:15], v[14:15], v[188:189], v[78:79] op_sel_hi:[1,0,1]
	v_cvt_pk_bf16_f32 v16, v12, v13
	v_mul_f32_e32 v13, v13, v13
	v_fmac_f32_e32 v13, v12, v12
	v_mul_f32_e32 v12, v15, v15
	v_fmac_f32_e32 v12, v14, v14
	s_waitcnt vmcnt(14)
	v_pk_fma_f32 v[8:9], v[8:9], v[188:189], v[72:73] op_sel_hi:[1,0,1]
	v_cvt_pk_bf16_f32 v17, v14, v15
	v_add_f32_e32 v14, v13, v12
	v_pk_fma_f32 v[10:11], v[10:11], v[188:189], v[74:75] op_sel_hi:[1,0,1]
	v_cvt_pk_bf16_f32 v12, v8, v9
	v_mul_f32_e32 v9, v9, v9
	v_fmac_f32_e32 v9, v8, v8
	v_mul_f32_e32 v8, v11, v11
	v_fmac_f32_e32 v8, v10, v10
	v_add_f32_e32 v8, v9, v8
	s_waitcnt vmcnt(13)
	v_pk_fma_f32 v[4:5], v[4:5], v[188:189], v[68:69] op_sel_hi:[1,0,1]
	v_cvt_pk_bf16_f32 v13, v10, v11
	v_add_f32_e32 v10, v14, v8
	v_pk_fma_f32 v[6:7], v[6:7], v[188:189], v[70:71] op_sel_hi:[1,0,1]
	v_cvt_pk_bf16_f32 v8, v4, v5
	v_mul_f32_e32 v5, v5, v5
	v_fmac_f32_e32 v5, v4, v4
	v_mul_f32_e32 v4, v7, v7
	v_fmac_f32_e32 v4, v6, v6
	s_waitcnt vmcnt(12)
	v_pk_fma_f32 v[2:3], v[2:3], v[188:189], v[66:67] op_sel_hi:[1,0,1]
	v_pk_fma_f32 v[0:1], v[0:1], v[188:189], v[64:65] op_sel_hi:[1,0,1]
	v_cvt_pk_bf16_f32 v9, v6, v7
	v_add_f32_e32 v4, v5, v4
	v_mul_f32_e32 v5, v1, v1
	v_mul_f32_e32 v6, v3, v3
	v_fmac_f32_e32 v5, v0, v0
	v_fmac_f32_e32 v6, v2, v2
	v_add_f32_e32 v4, v10, v4
	v_add_f32_e32 v5, v5, v6
	v_add_f32_e32 v4, v4, v5
	v_mov_b32_e32 v5, v4
	v_lshlrev_b64 v[18:19], 11, v[112:113]
	v_lshl_add_u64 v[18:19], s[14:15], 0, v[18:19]
	v_lshl_add_u64 v[18:19], v[192:193], 1, v[18:19]
	v_cvt_pk_bf16_f32 v0, v0, v1
	v_cvt_pk_bf16_f32 v1, v2, v3
	global_store_dwordx2 v[18:19], v[0:1], off offset:288
	s_waitcnt lgkmcnt(0)
	s_nop 1
	v_permlane16_swap_b32_e32 v4, v5
	v_add_f32_e32 v0, v4, v5
	v_mov_b32_e32 v1, v0
	s_nop 1
	v_permlane32_swap_b32_e32 v0, v1
	global_store_dwordx2 v[18:19], v[16:17], off
	global_store_dwordx2 v[18:19], v[12:13], off offset:32
	global_store_dwordx2 v[18:19], v[8:9], off offset:256
	s_and_saveexec_b64 s[40:41], vcc
	s_cbranch_execz .LBB0_719
	v_lshl_add_u64 v[2:3], v[112:113], 2, s[16:17]
	v_add_f32_e32 v0, v0, v1
	global_atomic_add_f32 v[2:3], v0, off

.Lalign_2:
	s_waitcnt vmcnt(0)
	v_lshlrev_b32_e32 v246, 16, v236
	v_and_b32_e32 v247, 0xffff0000, v236
	v_lshlrev_b32_e32 v236, 16, v237
	v_and_b32_e32 v237, 0xffff0000, v237
	v_lshlrev_b32_e32 v248, 16, v238
	v_and_b32_e32 v249, 0xffff0000, v238
	v_lshlrev_b32_e32 v238, 16, v239
	v_and_b32_e32 v239, 0xffff0000, v239
	v_pk_add_f32 v[134:135], v[134:135], v[236:237]
	v_pk_add_f32 v[132:133], v[132:133], v[246:247]
	v_pk_add_f32 v[236:237], v[130:131], v[238:239]
	v_pk_add_f32 v[238:239], v[128:129], v[248:249]
	v_cvt_pk_bf16_f32 v128, v132, v133
	v_cvt_pk_bf16_f32 v129, v134, v135
	v_cvt_pk_bf16_f32 v130, v238, v239
	v_cvt_pk_bf16_f32 v131, v236, v237
	v_mul_f32_e32 v133, v133, v133
	v_mul_f32_e32 v135, v135, v135
	v_mul_f32_e32 v239, v239, v239
	v_mul_f32_e32 v237, v237, v237
	v_fmac_f32_e32 v133, v132, v132
	v_fmac_f32_e32 v135, v134, v134
	v_fmac_f32_e32 v239, v238, v238
	v_fmac_f32_e32 v237, v236, v236
	global_store_dwordx4 v[244:245], v[128:131], off
	v_lshlrev_b32_e32 v132, 16, v242
	v_lshlrev_b32_e32 v134, 16, v243
	v_add_f32_e32 v128, v133, v135
	v_add_f32_e32 v129, v239, v237
	v_add_f32_e32 v236, v128, v129
	v_lshlrev_b32_e32 v128, 16, v240
	v_and_b32_e32 v129, 0xffff0000, v240
	v_lshlrev_b32_e32 v130, 16, v241
	v_and_b32_e32 v131, 0xffff0000, v241
	v_and_b32_e32 v133, 0xffff0000, v242
	v_and_b32_e32 v135, 0xffff0000, v243
	v_pk_add_f32 v[116:117], v[116:117], v[128:129]
	v_pk_add_f32 v[118:119], v[118:119], v[130:131]
	v_pk_add_f32 v[128:129], v[114:115], v[134:135]
	v_pk_add_f32 v[114:115], v[112:113], v[132:133]
	v_mul_f32_e32 v113, v117, v117
	v_cvt_pk_bf16_f32 v112, v116, v117
	v_fmac_f32_e32 v113, v116, v116
	v_mul_f32_e32 v116, v119, v119
	v_fmac_f32_e32 v116, v118, v118
	v_add_f32_e32 v113, v113, v116
	v_mul_f32_e32 v116, v115, v115
	v_mul_f32_e32 v117, v129, v129
	v_fmac_f32_e32 v116, v114, v114
	v_fmac_f32_e32 v117, v128, v128
	v_add_f32_e32 v116, v116, v117
	v_add_f32_e32 v113, v113, v116
	v_add_f32_e32 v116, v236, v113
	v_mov_b32_e32 v117, v116
	v_cvt_pk_bf16_f32 v113, v118, v119
	v_cvt_pk_bf16_f32 v114, v114, v115
	v_cvt_pk_bf16_f32 v115, v128, v129
	global_store_dwordx4 v[244:245], v[112:115], off offset:256
	s_waitcnt lgkmcnt(0)
	s_nop 0
	s_nop 1
	v_permlane16_swap_b32_e32 v116, v117
	v_add_f32_e32 v112, v116, v117
	v_mov_b32_e32 v113, v112
	s_nop 1
	v_permlane32_swap_b32_e32 v112, v113
	s_and_saveexec_b64 s[26:27], vcc
	s_cbranch_execz .LBB0_871
	v_lshl_add_u64 v[114:115], v[228:229], 2, s[16:17]
	v_add_f32_e32 v112, v112, v113
	global_atomic_add_f32 v[114:115], v112, off
.LBB0_871:
	s_or_b64 exec, exec, s[26:27]
	v_lshlrev_b32_e32 v112, 16, v180
	v_and_b32_e32 v113, 0xffff0000, v180
	v_lshlrev_b32_e32 v114, 16, v181
	v_and_b32_e32 v115, 0xffff0000, v181
	v_lshlrev_b32_e32 v116, 16, v182
	v_and_b32_e32 v117, 0xffff0000, v182
	v_lshlrev_b32_e32 v118, 16, v183
	v_and_b32_e32 v119, 0xffff0000, v183
	v_pk_add_f32 v[110:111], v[110:111], v[114:115]
	v_pk_add_f32 v[108:109], v[108:109], v[112:113]
	v_pk_add_f32 v[112:113], v[106:107], v[118:119]
	v_pk_add_f32 v[114:115], v[104:105], v[116:117]
	v_lshl_add_u64 v[104:105], s[14:15], 0, v[230:231]
	v_lshl_add_u64 v[116:117], v[206:207], 1, v[104:105]
	v_cvt_pk_bf16_f32 v104, v108, v109
	v_cvt_pk_bf16_f32 v105, v110, v111
	v_cvt_pk_bf16_f32 v106, v114, v115
	v_cvt_pk_bf16_f32 v107, v112, v113
	global_store_dwordx4 v[116:117], v[104:107], off
	s_nop 1
	v_mul_f32_e32 v104, v109, v109
	v_mul_f32_e32 v105, v111, v111
	v_fmac_f32_e32 v104, v108, v108
	v_fmac_f32_e32 v105, v110, v110
	v_add_f32_e32 v104, v104, v105
	v_mul_f32_e32 v105, v115, v115
	v_mul_f32_e32 v106, v113, v113
	v_fmac_f32_e32 v105, v114, v114
	v_fmac_f32_e32 v106, v112, v112
	v_add_f32_e32 v105, v105, v106
	v_add_f32_e32 v112, v104, v105
	v_lshlrev_b32_e32 v104, 16, v176
	v_and_b32_e32 v105, 0xffff0000, v176
	v_lshlrev_b32_e32 v106, 16, v177
	v_and_b32_e32 v107, 0xffff0000, v177
	v_lshlrev_b32_e32 v108, 16, v178
	v_and_b32_e32 v109, 0xffff0000, v178
	v_lshlrev_b32_e32 v110, 16, v179
	v_and_b32_e32 v111, 0xffff0000, v179
	v_pk_add_f32 v[100:101], v[100:101], v[104:105]
	v_pk_add_f32 v[102:103], v[102:103], v[106:107]
	v_pk_add_f32 v[104:105], v[98:99], v[110:111]
	v_pk_add_f32 v[98:99], v[96:97], v[108:109]
	v_mul_f32_e32 v97, v101, v101
	v_cvt_pk_bf16_f32 v96, v100, v101
	v_fmac_f32_e32 v97, v100, v100
	v_mul_f32_e32 v100, v103, v103
	v_fmac_f32_e32 v100, v102, v102
	v_add_f32_e32 v97, v97, v100
	v_mul_f32_e32 v100, v99, v99
	v_mul_f32_e32 v101, v105, v105
	v_fmac_f32_e32 v100, v98, v98
	v_fmac_f32_e32 v101, v104, v104
	v_add_f32_e32 v100, v100, v101
	v_add_f32_e32 v97, v97, v100
	v_add_f32_e32 v100, v112, v97
	v_mov_b32_e32 v101, v100
	v_cvt_pk_bf16_f32 v97, v102, v103
	v_cvt_pk_bf16_f32 v98, v98, v99
	v_cvt_pk_bf16_f32 v99, v104, v105
	global_store_dwordx4 v[116:117], v[96:99], off offset:256
	s_waitcnt lgkmcnt(0)
	s_nop 0
	s_nop 1
	v_permlane16_swap_b32_e32 v100, v101
	v_add_f32_e32 v96, v100, v101
	v_mov_b32_e32 v97, v96
	s_nop 1
	v_permlane32_swap_b32_e32 v96, v97
	s_and_saveexec_b64 s[26:27], vcc
	s_cbranch_execz .LBB0_873
	v_lshl_add_u64 v[98:99], v[224:225], 2, s[16:17]
	v_add_f32_e32 v96, v96, v97
	global_atomic_add_f32 v[98:99], v96, off
.LBB0_873:
	s_or_b64 exec, exec, s[26:27]
	v_lshlrev_b32_e32 v96, 16, v172
	v_and_b32_e32 v97, 0xffff0000, v172
	v_lshlrev_b32_e32 v98, 16, v173
	v_and_b32_e32 v99, 0xffff0000, v173
	v_lshlrev_b32_e32 v100, 16, v174
	v_and_b32_e32 v101, 0xffff0000, v174
	v_lshlrev_b32_e32 v102, 16, v175
	v_and_b32_e32 v103, 0xffff0000, v175
	v_pk_add_f32 v[94:95], v[94:95], v[98:99]
	v_pk_add_f32 v[92:93], v[92:93], v[96:97]
	v_pk_add_f32 v[96:97], v[90:91], v[102:103]
	v_pk_add_f32 v[98:99], v[88:89], v[100:101]
	v_lshl_add_u64 v[88:89], s[14:15], 0, v[226:227]
	v_lshl_add_u64 v[100:101], v[206:207], 1, v[88:89]
	v_cvt_pk_bf16_f32 v88, v92, v93
	v_cvt_pk_bf16_f32 v89, v94, v95
	v_cvt_pk_bf16_f32 v90, v98, v99
	v_cvt_pk_bf16_f32 v91, v96, v97
	global_store_dwordx4 v[100:101], v[88:91], off
	s_nop 1
	v_mul_f32_e32 v88, v93, v93
	v_mul_f32_e32 v89, v95, v95
	v_fmac_f32_e32 v88, v92, v92
	v_fmac_f32_e32 v89, v94, v94
	v_add_f32_e32 v88, v88, v89
	v_mul_f32_e32 v89, v99, v99
	v_mul_f32_e32 v90, v97, v97
	v_fmac_f32_e32 v89, v98, v98
	v_fmac_f32_e32 v90, v96, v96
	v_add_f32_e32 v89, v89, v90
	v_add_f32_e32 v96, v88, v89
	v_lshlrev_b32_e32 v88, 16, v168
	v_and_b32_e32 v89, 0xffff0000, v168
	v_lshlrev_b32_e32 v90, 16, v169
	v_and_b32_e32 v91, 0xffff0000, v169
	v_lshlrev_b32_e32 v92, 16, v170
	v_and_b32_e32 v93, 0xffff0000, v170
	v_lshlrev_b32_e32 v94, 16, v171
	v_and_b32_e32 v95, 0xffff0000, v171
	v_pk_add_f32 v[84:85], v[84:85], v[88:89]
	v_pk_add_f32 v[86:87], v[86:87], v[90:91]
	v_pk_add_f32 v[88:89], v[82:83], v[94:95]
	v_pk_add_f32 v[82:83], v[80:81], v[92:93]
	v_mul_f32_e32 v81, v85, v85
	v_cvt_pk_bf16_f32 v80, v84, v85
	v_fmac_f32_e32 v81, v84, v84
	v_mul_f32_e32 v84, v87, v87
	v_fmac_f32_e32 v84, v86, v86
	v_add_f32_e32 v81, v81, v84
	v_mul_f32_e32 v84, v83, v83
	v_mul_f32_e32 v85, v89, v89
	v_fmac_f32_e32 v84, v82, v82
	v_fmac_f32_e32 v85, v88, v88
	v_add_f32_e32 v84, v84, v85
	v_add_f32_e32 v81, v81, v84
	v_add_f32_e32 v84, v96, v81
	v_mov_b32_e32 v85, v84
	v_cvt_pk_bf16_f32 v81, v86, v87
	v_cvt_pk_bf16_f32 v82, v82, v83
	v_cvt_pk_bf16_f32 v83, v88, v89
	global_store_dwordx4 v[100:101], v[80:83], off offset:256
	s_waitcnt lgkmcnt(0)
	s_nop 0
	s_nop 1
	v_permlane16_swap_b32_e32 v84, v85
	v_add_f32_e32 v80, v84, v85
	v_mov_b32_e32 v81, v80
	s_nop 1
	v_permlane32_swap_b32_e32 v80, v81
	s_and_saveexec_b64 s[26:27], vcc
	s_cbranch_execz .LBB0_875
	v_lshl_add_u64 v[82:83], v[220:221], 2, s[16:17]
	v_add_f32_e32 v80, v80, v81
	global_atomic_add_f32 v[82:83], v80, off
.LBB0_875:
	s_or_b64 exec, exec, s[26:27]
	v_lshlrev_b32_e32 v80, 16, v164
	v_and_b32_e32 v81, 0xffff0000, v164
	v_lshlrev_b32_e32 v82, 16, v165
	v_and_b32_e32 v83, 0xffff0000, v165
	v_lshlrev_b32_e32 v84, 16, v166
	v_and_b32_e32 v85, 0xffff0000, v166
	v_lshlrev_b32_e32 v86, 16, v167
	v_and_b32_e32 v87, 0xffff0000, v167
	v_pk_add_f32 v[78:79], v[78:79], v[82:83]
	v_pk_add_f32 v[76:77], v[76:77], v[80:81]
	v_pk_add_f32 v[80:81], v[74:75], v[86:87]
	v_pk_add_f32 v[82:83], v[72:73], v[84:85]
	v_lshl_add_u64 v[72:73], s[14:15], 0, v[222:223]
	v_lshl_add_u64 v[84:85], v[206:207], 1, v[72:73]
	v_cvt_pk_bf16_f32 v72, v76, v77
	v_cvt_pk_bf16_f32 v73, v78, v79
	v_cvt_pk_bf16_f32 v74, v82, v83
	v_cvt_pk_bf16_f32 v75, v80, v81
	global_store_dwordx4 v[84:85], v[72:75], off
	s_nop 1
	v_mul_f32_e32 v72, v77, v77
	v_mul_f32_e32 v73, v79, v79
	v_fmac_f32_e32 v72, v76, v76
	v_fmac_f32_e32 v73, v78, v78
	v_add_f32_e32 v72, v72, v73
	v_mul_f32_e32 v73, v83, v83
	v_mul_f32_e32 v74, v81, v81
	v_fmac_f32_e32 v73, v82, v82
	v_fmac_f32_e32 v74, v80, v80
	v_add_f32_e32 v73, v73, v74
	v_add_f32_e32 v80, v72, v73
	v_lshlrev_b32_e32 v72, 16, v160
	v_and_b32_e32 v73, 0xffff0000, v160
	v_lshlrev_b32_e32 v74, 16, v161
	v_and_b32_e32 v75, 0xffff0000, v161
	v_lshlrev_b32_e32 v76, 16, v162
	v_and_b32_e32 v77, 0xffff0000, v162
	v_lshlrev_b32_e32 v78, 16, v163
	v_and_b32_e32 v79, 0xffff0000, v163
	v_pk_add_f32 v[68:69], v[68:69], v[72:73]
	v_pk_add_f32 v[70:71], v[70:71], v[74:75]
	v_pk_add_f32 v[72:73], v[66:67], v[78:79]
	v_pk_add_f32 v[66:67], v[64:65], v[76:77]
	v_mul_f32_e32 v65, v69, v69
	v_cvt_pk_bf16_f32 v64, v68, v69
	v_fmac_f32_e32 v65, v68, v68
	v_mul_f32_e32 v68, v71, v71
	v_fmac_f32_e32 v68, v70, v70
	v_add_f32_e32 v65, v65, v68
	v_mul_f32_e32 v68, v67, v67
	v_mul_f32_e32 v69, v73, v73
	v_fmac_f32_e32 v68, v66, v66
	v_fmac_f32_e32 v69, v72, v72
	v_add_f32_e32 v68, v68, v69
	v_add_f32_e32 v65, v65, v68
	v_add_f32_e32 v68, v80, v65
	v_mov_b32_e32 v69, v68
	v_cvt_pk_bf16_f32 v65, v70, v71
	v_cvt_pk_bf16_f32 v66, v66, v67
	v_cvt_pk_bf16_f32 v67, v72, v73
	global_store_dwordx4 v[84:85], v[64:67], off offset:256
	s_waitcnt lgkmcnt(0)
	s_nop 0
	s_nop 1
	v_permlane16_swap_b32_e32 v68, v69
	v_add_f32_e32 v64, v68, v69
	v_mov_b32_e32 v65, v64
	s_nop 1
	v_permlane32_swap_b32_e32 v64, v65
	s_and_saveexec_b64 s[26:27], vcc
	s_cbranch_execz .LBB0_877
	v_lshl_add_u64 v[66:67], v[216:217], 2, s[16:17]
	v_add_f32_e32 v64, v64, v65
	global_atomic_add_f32 v[66:67], v64, off
.LBB0_877:
	s_or_b64 exec, exec, s[26:27]
	v_lshlrev_b32_e32 v64, 16, v156
	v_and_b32_e32 v65, 0xffff0000, v156
	v_lshlrev_b32_e32 v66, 16, v157
	v_and_b32_e32 v67, 0xffff0000, v157
	v_lshlrev_b32_e32 v68, 16, v158
	v_and_b32_e32 v69, 0xffff0000, v158
	v_lshlrev_b32_e32 v70, 16, v159
	v_and_b32_e32 v71, 0xffff0000, v159
	v_pk_add_f32 v[62:63], v[62:63], v[66:67]
	v_pk_add_f32 v[60:61], v[60:61], v[64:65]
	v_pk_add_f32 v[64:65], v[58:59], v[70:71]
	v_pk_add_f32 v[66:67], v[56:57], v[68:69]
	v_lshl_add_u64 v[56:57], s[14:15], 0, v[218:219]
	v_lshl_add_u64 v[68:69], v[206:207], 1, v[56:57]
	v_cvt_pk_bf16_f32 v56, v60, v61
	v_cvt_pk_bf16_f32 v57, v62, v63
	v_cvt_pk_bf16_f32 v58, v66, v67
	v_cvt_pk_bf16_f32 v59, v64, v65
	global_store_dwordx4 v[68:69], v[56:59], off
	s_nop 1
	v_mul_f32_e32 v56, v61, v61
	v_mul_f32_e32 v57, v63, v63
	v_fmac_f32_e32 v56, v60, v60
	v_fmac_f32_e32 v57, v62, v62
	v_add_f32_e32 v56, v56, v57
	v_mul_f32_e32 v57, v67, v67
	v_mul_f32_e32 v58, v65, v65
	v_fmac_f32_e32 v57, v66, v66
	v_fmac_f32_e32 v58, v64, v64
	v_add_f32_e32 v57, v57, v58
	v_add_f32_e32 v64, v56, v57
	v_lshlrev_b32_e32 v56, 16, v152
	v_and_b32_e32 v57, 0xffff0000, v152
	v_lshlrev_b32_e32 v58, 16, v153
	v_and_b32_e32 v59, 0xffff0000, v153
	v_lshlrev_b32_e32 v60, 16, v154
	v_and_b32_e32 v61, 0xffff0000, v154
	v_lshlrev_b32_e32 v62, 16, v155
	v_and_b32_e32 v63, 0xffff0000, v155
	v_pk_add_f32 v[52:53], v[52:53], v[56:57]
	v_pk_add_f32 v[54:55], v[54:55], v[58:59]
	v_pk_add_f32 v[56:57], v[50:51], v[62:63]
	v_pk_add_f32 v[50:51], v[48:49], v[60:61]
	v_mul_f32_e32 v49, v53, v53
	v_cvt_pk_bf16_f32 v48, v52, v53
	v_fmac_f32_e32 v49, v52, v52
	v_mul_f32_e32 v52, v55, v55
	v_fmac_f32_e32 v52, v54, v54
	v_add_f32_e32 v49, v49, v52
	v_mul_f32_e32 v52, v51, v51
	v_mul_f32_e32 v53, v57, v57
	v_fmac_f32_e32 v52, v50, v50
	v_fmac_f32_e32 v53, v56, v56
	v_add_f32_e32 v52, v52, v53
	v_add_f32_e32 v49, v49, v52
	v_add_f32_e32 v52, v64, v49
	v_mov_b32_e32 v53, v52
	v_cvt_pk_bf16_f32 v49, v54, v55
	v_cvt_pk_bf16_f32 v50, v50, v51
	v_cvt_pk_bf16_f32 v51, v56, v57
	global_store_dwordx4 v[68:69], v[48:51], off offset:256
	s_waitcnt lgkmcnt(0)
	s_nop 0
	s_nop 1
	v_permlane16_swap_b32_e32 v52, v53
	v_add_f32_e32 v48, v52, v53
	v_mov_b32_e32 v49, v48
	s_nop 1
	v_permlane32_swap_b32_e32 v48, v49
	s_and_saveexec_b64 s[26:27], vcc
	s_cbranch_execz .LBB0_879
	v_lshl_add_u64 v[50:51], v[212:213], 2, s[16:17]
	v_add_f32_e32 v48, v48, v49
	global_atomic_add_f32 v[50:51], v48, off
.LBB0_879:
	s_or_b64 exec, exec, s[26:27]
	v_lshlrev_b32_e32 v48, 16, v148
	v_and_b32_e32 v49, 0xffff0000, v148
	v_lshlrev_b32_e32 v50, 16, v149
	v_and_b32_e32 v51, 0xffff0000, v149
	v_lshlrev_b32_e32 v52, 16, v150
	v_and_b32_e32 v53, 0xffff0000, v150
	v_lshlrev_b32_e32 v54, 16, v151
	v_and_b32_e32 v55, 0xffff0000, v151
	v_pk_add_f32 v[46:47], v[46:47], v[50:51]
	v_pk_add_f32 v[44:45], v[44:45], v[48:49]
	v_pk_add_f32 v[48:49], v[42:43], v[54:55]
	v_pk_add_f32 v[50:51], v[40:41], v[52:53]
	v_lshl_add_u64 v[40:41], s[14:15], 0, v[214:215]
	v_lshl_add_u64 v[52:53], v[206:207], 1, v[40:41]
	v_cvt_pk_bf16_f32 v40, v44, v45
	v_cvt_pk_bf16_f32 v41, v46, v47
	v_cvt_pk_bf16_f32 v42, v50, v51
	v_cvt_pk_bf16_f32 v43, v48, v49
	global_store_dwordx4 v[52:53], v[40:43], off
	s_nop 1
	v_mul_f32_e32 v40, v45, v45
	v_mul_f32_e32 v41, v47, v47
	v_fmac_f32_e32 v40, v44, v44
	v_fmac_f32_e32 v41, v46, v46
	v_add_f32_e32 v40, v40, v41
	v_mul_f32_e32 v41, v51, v51
	v_mul_f32_e32 v42, v49, v49
	v_fmac_f32_e32 v41, v50, v50
	v_fmac_f32_e32 v42, v48, v48
	v_add_f32_e32 v41, v41, v42
	v_add_f32_e32 v48, v40, v41
	v_lshlrev_b32_e32 v40, 16, v144
	v_and_b32_e32 v41, 0xffff0000, v144
	v_lshlrev_b32_e32 v42, 16, v145
	v_and_b32_e32 v43, 0xffff0000, v145
	v_lshlrev_b32_e32 v44, 16, v146
	v_and_b32_e32 v45, 0xffff0000, v146
	v_lshlrev_b32_e32 v46, 16, v147
	v_and_b32_e32 v47, 0xffff0000, v147
	v_pk_add_f32 v[36:37], v[36:37], v[40:41]
	v_pk_add_f32 v[38:39], v[38:39], v[42:43]
	v_pk_add_f32 v[40:41], v[34:35], v[46:47]
	v_pk_add_f32 v[34:35], v[32:33], v[44:45]
	v_mul_f32_e32 v33, v37, v37
	v_cvt_pk_bf16_f32 v32, v36, v37
	v_fmac_f32_e32 v33, v36, v36
	v_mul_f32_e32 v36, v39, v39
	v_fmac_f32_e32 v36, v38, v38
	v_add_f32_e32 v33, v33, v36
	v_mul_f32_e32 v36, v35, v35
	v_mul_f32_e32 v37, v41, v41
	v_fmac_f32_e32 v36, v34, v34
	v_fmac_f32_e32 v37, v40, v40
	v_add_f32_e32 v36, v36, v37
	v_add_f32_e32 v33, v33, v36
	v_add_f32_e32 v36, v48, v33
	v_mov_b32_e32 v37, v36
	v_cvt_pk_bf16_f32 v33, v38, v39
	v_cvt_pk_bf16_f32 v34, v34, v35
	v_cvt_pk_bf16_f32 v35, v40, v41
	global_store_dwordx4 v[52:53], v[32:35], off offset:256
	s_waitcnt lgkmcnt(0)
	s_nop 0
	s_nop 1
	v_permlane16_swap_b32_e32 v36, v37
	v_add_f32_e32 v32, v36, v37
	v_mov_b32_e32 v33, v32
	s_nop 1
	v_permlane32_swap_b32_e32 v32, v33
	s_and_saveexec_b64 s[26:27], vcc
	s_cbranch_execz .LBB0_881
	v_lshl_add_u64 v[34:35], v[208:209], 2, s[16:17]
	v_add_f32_e32 v32, v32, v33
	global_atomic_add_f32 v[34:35], v32, off
.LBB0_881:
	s_or_b64 exec, exec, s[26:27]
	v_lshlrev_b32_e32 v32, 16, v140
	v_and_b32_e32 v33, 0xffff0000, v140
	v_lshlrev_b32_e32 v34, 16, v141
	v_and_b32_e32 v35, 0xffff0000, v141
	v_lshlrev_b32_e32 v36, 16, v142
	v_and_b32_e32 v37, 0xffff0000, v142
	v_lshlrev_b32_e32 v38, 16, v143
	v_and_b32_e32 v39, 0xffff0000, v143
	v_pk_add_f32 v[30:31], v[30:31], v[34:35]
	v_pk_add_f32 v[28:29], v[28:29], v[32:33]
	v_pk_add_f32 v[32:33], v[26:27], v[38:39]
	v_pk_add_f32 v[34:35], v[24:25], v[36:37]
	v_lshl_add_u64 v[24:25], s[14:15], 0, v[210:211]
	v_lshl_add_u64 v[36:37], v[206:207], 1, v[24:25]
	v_cvt_pk_bf16_f32 v24, v28, v29
	v_cvt_pk_bf16_f32 v25, v30, v31
	v_cvt_pk_bf16_f32 v26, v34, v35
	v_cvt_pk_bf16_f32 v27, v32, v33
	global_store_dwordx4 v[36:37], v[24:27], off
	s_nop 1
	v_mul_f32_e32 v24, v29, v29
	v_mul_f32_e32 v25, v31, v31
	v_fmac_f32_e32 v24, v28, v28
	v_fmac_f32_e32 v25, v30, v30
	v_add_f32_e32 v24, v24, v25
	v_mul_f32_e32 v25, v35, v35
	v_mul_f32_e32 v26, v33, v33
	v_fmac_f32_e32 v25, v34, v34
	v_fmac_f32_e32 v26, v32, v32
	v_add_f32_e32 v25, v25, v26
	v_add_f32_e32 v32, v24, v25
	v_lshlrev_b32_e32 v24, 16, v136
	v_and_b32_e32 v25, 0xffff0000, v136
	v_lshlrev_b32_e32 v26, 16, v137
	v_and_b32_e32 v27, 0xffff0000, v137
	v_lshlrev_b32_e32 v28, 16, v138
	v_and_b32_e32 v29, 0xffff0000, v138
	v_lshlrev_b32_e32 v30, 16, v139
	v_and_b32_e32 v31, 0xffff0000, v139
	v_pk_add_f32 v[20:21], v[20:21], v[24:25]
	v_pk_add_f32 v[22:23], v[22:23], v[26:27]
	v_pk_add_f32 v[24:25], v[18:19], v[30:31]
	v_pk_add_f32 v[18:19], v[16:17], v[28:29]
	v_mul_f32_e32 v17, v21, v21
	v_cvt_pk_bf16_f32 v16, v20, v21
	v_fmac_f32_e32 v17, v20, v20
	v_mul_f32_e32 v20, v23, v23
	v_fmac_f32_e32 v20, v22, v22
	v_add_f32_e32 v17, v17, v20
	v_mul_f32_e32 v20, v19, v19
	v_mul_f32_e32 v21, v25, v25
	v_fmac_f32_e32 v20, v18, v18
	v_fmac_f32_e32 v21, v24, v24
	v_add_f32_e32 v20, v20, v21
	v_add_f32_e32 v17, v17, v20
	v_add_f32_e32 v20, v32, v17
	v_mov_b32_e32 v21, v20
	v_cvt_pk_bf16_f32 v17, v22, v23
	v_cvt_pk_bf16_f32 v18, v18, v19
	v_cvt_pk_bf16_f32 v19, v24, v25
	global_store_dwordx4 v[36:37], v[16:19], off offset:256
	s_waitcnt lgkmcnt(0)
	s_nop 0
	s_nop 1
	v_permlane16_swap_b32_e32 v20, v21
	v_add_f32_e32 v16, v20, v21
	v_mov_b32_e32 v17, v16
	s_nop 1
	v_permlane32_swap_b32_e32 v16, v17
	s_and_saveexec_b64 s[26:27], vcc
	s_cbranch_execz .LBB0_883
	v_lshl_add_u64 v[18:19], v[204:205], 2, s[16:17]
	v_add_f32_e32 v16, v16, v17
	global_atomic_add_f32 v[18:19], v16, off
.LBB0_883:
	s_or_b64 exec, exec, s[26:27]
	v_lshlrev_b32_e32 v16, 16, v124
	v_and_b32_e32 v17, 0xffff0000, v124
	v_lshlrev_b32_e32 v18, 16, v125
	v_and_b32_e32 v19, 0xffff0000, v125
	v_lshlrev_b32_e32 v20, 16, v126
	v_and_b32_e32 v21, 0xffff0000, v126
	v_lshlrev_b32_e32 v22, 16, v127
	v_and_b32_e32 v23, 0xffff0000, v127
	v_pk_add_f32 v[14:15], v[14:15], v[18:19]
	v_pk_add_f32 v[12:13], v[12:13], v[16:17]
	v_pk_add_f32 v[16:17], v[10:11], v[22:23]
	v_pk_add_f32 v[18:19], v[8:9], v[20:21]
	v_lshl_add_u64 v[8:9], s[14:15], 0, v[202:203]
	v_lshl_add_u64 v[20:21], v[206:207], 1, v[8:9]
	v_cvt_pk_bf16_f32 v8, v12, v13
	v_cvt_pk_bf16_f32 v9, v14, v15
	v_cvt_pk_bf16_f32 v10, v18, v19
	v_cvt_pk_bf16_f32 v11, v16, v17
	global_store_dwordx4 v[20:21], v[8:11], off
	s_nop 1
	v_mul_f32_e32 v8, v13, v13
	v_mul_f32_e32 v9, v15, v15
	v_fmac_f32_e32 v8, v12, v12
	v_fmac_f32_e32 v9, v14, v14
	v_add_f32_e32 v8, v8, v9
	v_mul_f32_e32 v9, v19, v19
	v_mul_f32_e32 v10, v17, v17
	v_fmac_f32_e32 v9, v18, v18
	v_fmac_f32_e32 v10, v16, v16
	v_add_f32_e32 v9, v9, v10
	v_add_f32_e32 v16, v8, v9
	v_lshlrev_b32_e32 v8, 16, v120
	v_and_b32_e32 v9, 0xffff0000, v120
	v_lshlrev_b32_e32 v10, 16, v121
	v_and_b32_e32 v11, 0xffff0000, v121
	v_lshlrev_b32_e32 v12, 16, v122
	v_and_b32_e32 v13, 0xffff0000, v122
	v_lshlrev_b32_e32 v14, 16, v123
	v_and_b32_e32 v15, 0xffff0000, v123
	v_pk_add_f32 v[4:5], v[4:5], v[8:9]
	v_pk_add_f32 v[6:7], v[6:7], v[10:11]
	v_pk_add_f32 v[8:9], v[2:3], v[14:15]
	v_pk_add_f32 v[2:3], v[0:1], v[12:13]
	v_mul_f32_e32 v1, v5, v5
	v_cvt_pk_bf16_f32 v0, v4, v5
	v_fmac_f32_e32 v1, v4, v4
	v_mul_f32_e32 v4, v7, v7
	v_fmac_f32_e32 v4, v6, v6
	v_add_f32_e32 v1, v1, v4
	v_mul_f32_e32 v4, v3, v3
	v_mul_f32_e32 v5, v9, v9
	v_fmac_f32_e32 v4, v2, v2
	v_fmac_f32_e32 v5, v8, v8
	v_add_f32_e32 v4, v4, v5
	v_add_f32_e32 v1, v1, v4
	v_add_f32_e32 v4, v16, v1
	v_mov_b32_e32 v5, v4
	v_cvt_pk_bf16_f32 v1, v6, v7
	v_cvt_pk_bf16_f32 v2, v2, v3
	v_cvt_pk_bf16_f32 v3, v8, v9
	global_store_dwordx4 v[20:21], v[0:3], off offset:256
	s_waitcnt lgkmcnt(0)
	s_nop 0
	s_nop 1
	v_permlane16_swap_b32_e32 v4, v5
	v_add_f32_e32 v0, v4, v5
	v_mov_b32_e32 v1, v0
	s_nop 1
	v_permlane32_swap_b32_e32 v0, v1
	s_and_saveexec_b64 s[26:27], vcc
	s_cbranch_execz .LBB0_885
	v_lshl_add_u64 v[2:3], v[200:201], 2, s[16:17]
	v_add_f32_e32 v0, v0, v1
	global_atomic_add_f32 v[2:3], v0, off

.Lalign_3:
	s_waitcnt vmcnt(0)
	v_fmamk_f32 v191, v191, 0x3a800000, v182
	v_rsq_f32_e32 v192, v191
	s_nop 0
	v_pk_mul_f32 v[126:127], v[126:127], v[192:193] op_sel_hi:[1,0]
	v_pk_mul_f32 v[124:125], v[124:125], v[192:193] op_sel_hi:[1,0]
	v_pk_mul_f32 v[122:123], v[122:123], v[192:193] op_sel_hi:[1,0]
	v_pk_mul_f32 v[120:121], v[120:121], v[192:193] op_sel_hi:[1,0]
	v_pk_mul_f32 v[118:119], v[118:119], v[192:193] op_sel_hi:[1,0]
	v_pk_mul_f32 v[116:117], v[116:117], v[192:193] op_sel_hi:[1,0]
	v_pk_mul_f32 v[114:115], v[114:115], v[192:193] op_sel_hi:[1,0]
	v_pk_mul_f32 v[112:113], v[112:113], v[192:193] op_sel_hi:[1,0]
	s_cbranch_vccz .LBB0_965
	v_pk_mul_f32 v[192:193], v[126:127], v[126:127]
	v_pk_mul_f32 v[194:195], v[124:125], v[124:125]
	s_and_b64 s[6:7], s[40:41], exec
	v_pk_mov_b32 v[196:197], v[194:195], v[192:193] op_sel:[1,0]
	v_mov_b32_e32 v195, v193
	v_pk_add_f32 v[192:193], v[196:197], v[194:195]
	v_pk_mul_f32 v[194:195], v[122:123], v[122:123]
	v_pk_add_f32 v[192:193], v[192:193], v[192:193] op_sel_hi:[0,1]
	v_pk_mul_f32 v[196:197], v[120:121], v[120:121]
	v_mul_f32_e32 v192, v116, v116
	v_pk_mov_b32 v[198:199], v[196:197], v[194:195] op_sel:[1,0]
	v_mov_b32_e32 v197, v195
	v_pk_add_f32 v[194:195], v[198:199], v[196:197]
	v_pk_fma_f32 v[196:197], v[116:117], v[116:117], v[192:193] op_sel_hi:[1,1,0]
	v_mul_f32_e32 v192, v118, v118
	v_pk_add_f32 v[194:195], v[194:195], v[194:195] op_sel_hi:[0,1]
	v_pk_fma_f32 v[198:199], v[118:119], v[118:119], v[192:193] op_sel_hi:[1,1,0]
	v_mul_f32_e32 v196, v112, v112
	v_mul_f32_e32 v198, v113, v113
	v_mul_f32_e32 v192, v114, v114
	v_mul_f32_e32 v194, v115, v115
	v_pk_add_f32 v[196:197], v[196:197], v[198:199]
	v_pk_add_f32 v[192:193], v[192:193], v[194:195]
	s_cselect_b32 s7, s59, s61
	v_pk_add_f32 v[192:193], v[196:197], v[192:193]
	s_cselect_b32 s6, s58, s60
	v_add_f32_e32 v191, v192, v193
	v_mov_b32_e32 v192, v191
	v_pk_mul_f32 v[194:195], v[148:149], v[124:125]
	v_pk_mul_f32 v[202:203], v[146:147], v[120:121]
	s_waitcnt lgkmcnt(0)
	s_nop 1
	v_permlane16_swap_b32_e32 v191, v192
	v_add_f32_e32 v191, v191, v192
	v_mov_b32_e32 v192, v191
	s_nop 1
	v_permlane32_swap_b32_e32 v191, v192
	v_add_f32_e32 v191, v191, v192
	v_fmamk_f32 v191, v191, 0x3c800000, v182
	v_rsq_f32_e32 v196, v191
	v_lshlrev_b64 v[192:193], 11, v[176:177]
	v_lshl_add_u64 v[192:193], s[6:7], 0, v[192:193]
	s_lshl_b32 s6, s29, 1
	s_mov_b32 s7, s15
	v_lshl_add_u64 v[192:193], v[192:193], 0, s[6:7]
	v_lshl_add_u64 v[198:199], v[144:145], 1, v[192:193]
	v_pk_mul_f32 v[192:193], v[150:151], v[126:127]
	s_mov_b64 s[6:7], 0
	v_pk_mul_f32 v[200:201], v[192:193], v[196:197] op_sel_hi:[1,0]
	v_pk_mul_f32 v[192:193], v[194:195], v[196:197] op_sel_hi:[1,0]
	v_pk_mul_f32 v[194:195], v[152:153], v[122:123]
	v_cvt_pk_bf16_f32 v192, v192, v193
	v_pk_mul_f32 v[204:205], v[194:195], v[196:197] op_sel_hi:[1,0]
	v_pk_mul_f32 v[194:195], v[202:203], v[196:197] op_sel_hi:[1,0]
	v_cvt_pk_bf16_f32 v193, v200, v201
	v_cvt_pk_bf16_f32 v194, v194, v195
	v_cvt_pk_bf16_f32 v195, v204, v205
	global_store_dwordx4 v[198:199], v[192:195], off
	v_pk_mul_f32 v[202:203], v[154:155], v[112:113]
	s_nop 0
	v_pk_mul_f32 v[192:193], v[158:159], v[118:119]
	v_pk_mul_f32 v[194:195], v[156:157], v[116:117]
	v_pk_mul_f32 v[200:201], v[192:193], v[196:197] op_sel_hi:[1,0]
	v_pk_mul_f32 v[192:193], v[194:195], v[196:197] op_sel_hi:[1,0]
	v_pk_mul_f32 v[194:195], v[160:161], v[114:115]
	v_cvt_pk_bf16_f32 v192, v192, v193
	v_pk_mul_f32 v[204:205], v[194:195], v[196:197] op_sel_hi:[1,0]
	v_pk_mul_f32 v[194:195], v[202:203], v[196:197] op_sel_hi:[1,0]
	v_cvt_pk_bf16_f32 v193, v200, v201
	v_cvt_pk_bf16_f32 v194, v194, v195
	v_cvt_pk_bf16_f32 v195, v204, v205
	global_store_dwordx4 v[198:199], v[192:195], off offset:64

.LBB0_967:
	v_fmamk_f32 v112, v190, 0x3a800000, v182
	v_rsq_f32_e32 v112, v112
	s_andn2_b64 vcc, exec, s[42:43]
	s_mov_b64 s[38:39], -1
	v_pk_mul_f32 v[110:111], v[110:111], v[112:113] op_sel_hi:[1,0]
	v_pk_mul_f32 v[108:109], v[108:109], v[112:113] op_sel_hi:[1,0]
	v_pk_mul_f32 v[106:107], v[106:107], v[112:113] op_sel_hi:[1,0]
	v_pk_mul_f32 v[104:105], v[104:105], v[112:113] op_sel_hi:[1,0]
	v_pk_mul_f32 v[102:103], v[102:103], v[112:113] op_sel_hi:[1,0]
	v_pk_mul_f32 v[100:101], v[100:101], v[112:113] op_sel_hi:[1,0]
	v_pk_mul_f32 v[98:99], v[98:99], v[112:113] op_sel_hi:[1,0]
	v_pk_mul_f32 v[96:97], v[96:97], v[112:113] op_sel_hi:[1,0]
	v_cndmask_b32_e64 v112, 0, 1, s[42:43]
	v_cmp_ne_u32_e64 s[6:7], 1, v112
	s_cbranch_vccnz .LBB0_969
	v_pk_mul_f32 v[112:113], v[110:111], v[110:111]
	v_pk_mul_f32 v[114:115], v[108:109], v[108:109]
	s_and_b64 s[38:39], s[40:41], exec
	v_pk_mov_b32 v[116:117], v[114:115], v[112:113] op_sel:[1,0]
	v_mov_b32_e32 v115, v113
	v_pk_add_f32 v[112:113], v[116:117], v[114:115]
	v_pk_mul_f32 v[114:115], v[106:107], v[106:107]
	v_pk_add_f32 v[112:113], v[112:113], v[112:113] op_sel_hi:[0,1]
	v_pk_mul_f32 v[116:117], v[104:105], v[104:105]
	v_mul_f32_e32 v112, v100, v100
	v_pk_mov_b32 v[118:119], v[116:117], v[114:115] op_sel:[1,0]
	v_mov_b32_e32 v117, v115
	v_pk_add_f32 v[114:115], v[118:119], v[116:117]
	v_pk_fma_f32 v[116:117], v[100:101], v[100:101], v[112:113] op_sel_hi:[1,1,0]
	v_mul_f32_e32 v112, v102, v102
	v_pk_add_f32 v[114:115], v[114:115], v[114:115] op_sel_hi:[0,1]
	v_pk_fma_f32 v[118:119], v[102:103], v[102:103], v[112:113] op_sel_hi:[1,1,0]
	v_mul_f32_e32 v116, v96, v96
	v_mul_f32_e32 v118, v97, v97
	v_mul_f32_e32 v112, v98, v98
	v_mul_f32_e32 v114, v99, v99
	v_pk_add_f32 v[116:117], v[116:117], v[118:119]
	v_pk_add_f32 v[112:113], v[112:113], v[114:115]
	s_cselect_b32 s39, s59, s61
	v_pk_add_f32 v[112:113], v[116:117], v[112:113]
	s_cselect_b32 s38, s58, s60
	v_add_f32_e32 v112, v112, v113
	v_mov_b32_e32 v113, v112
	v_pk_mul_f32 v[114:115], v[148:149], v[108:109]
	v_pk_mul_f32 v[122:123], v[146:147], v[104:105]
	s_waitcnt lgkmcnt(0)
	s_nop 1
	v_permlane16_swap_b32_e32 v112, v113
	v_add_f32_e32 v112, v112, v113
	v_mov_b32_e32 v113, v112
	s_nop 1
	v_permlane32_swap_b32_e32 v112, v113
	v_add_f32_e32 v112, v112, v113
	v_fmamk_f32 v112, v112, 0x3c800000, v182
	v_rsq_f32_e32 v116, v112
	v_lshlrev_b64 v[112:113], 11, v[174:175]
	v_lshl_add_u64 v[112:113], s[38:39], 0, v[112:113]
	s_lshl_b32 s38, s29, 1
	s_mov_b32 s39, s15
	v_lshl_add_u64 v[112:113], v[112:113], 0, s[38:39]
	v_lshl_add_u64 v[118:119], v[144:145], 1, v[112:113]
	v_pk_mul_f32 v[112:113], v[150:151], v[110:111]
	s_mov_b64 s[38:39], 0
	v_pk_mul_f32 v[120:121], v[112:113], v[116:117] op_sel_hi:[1,0]
	v_pk_mul_f32 v[112:113], v[114:115], v[116:117] op_sel_hi:[1,0]
	v_pk_mul_f32 v[114:115], v[152:153], v[106:107]
	v_cvt_pk_bf16_f32 v112, v112, v113
	v_pk_mul_f32 v[124:125], v[114:115], v[116:117] op_sel_hi:[1,0]
	v_pk_mul_f32 v[114:115], v[122:123], v[116:117] op_sel_hi:[1,0]
	v_cvt_pk_bf16_f32 v113, v120, v121
	v_cvt_pk_bf16_f32 v114, v114, v115
	v_cvt_pk_bf16_f32 v115, v124, v125
	global_store_dwordx4 v[118:119], v[112:115], off
	v_pk_mul_f32 v[122:123], v[154:155], v[96:97]
	s_nop 0
	v_pk_mul_f32 v[112:113], v[158:159], v[102:103]
	v_pk_mul_f32 v[114:115], v[156:157], v[100:101]
	v_pk_mul_f32 v[120:121], v[112:113], v[116:117] op_sel_hi:[1,0]
	v_pk_mul_f32 v[112:113], v[114:115], v[116:117] op_sel_hi:[1,0]
	v_pk_mul_f32 v[114:115], v[160:161], v[98:99]
	v_cvt_pk_bf16_f32 v112, v112, v113
	v_pk_mul_f32 v[124:125], v[114:115], v[116:117] op_sel_hi:[1,0]
	v_pk_mul_f32 v[114:115], v[122:123], v[116:117] op_sel_hi:[1,0]
	v_cvt_pk_bf16_f32 v113, v120, v121
	v_cvt_pk_bf16_f32 v114, v114, v115
	v_cvt_pk_bf16_f32 v115, v124, v125
	global_store_dwordx4 v[118:119], v[112:115], off offset:64

.LBB0_971:
	v_fmamk_f32 v96, v189, 0x3a800000, v182
	v_rsq_f32_e32 v96, v96
	s_and_b64 vcc, exec, s[6:7]
	s_mov_b64 s[38:39], -1
	v_pk_mul_f32 v[94:95], v[94:95], v[96:97] op_sel_hi:[1,0]
	v_pk_mul_f32 v[92:93], v[92:93], v[96:97] op_sel_hi:[1,0]
	v_pk_mul_f32 v[90:91], v[90:91], v[96:97] op_sel_hi:[1,0]
	v_pk_mul_f32 v[88:89], v[88:89], v[96:97] op_sel_hi:[1,0]
	v_pk_mul_f32 v[86:87], v[86:87], v[96:97] op_sel_hi:[1,0]
	v_pk_mul_f32 v[84:85], v[84:85], v[96:97] op_sel_hi:[1,0]
	v_pk_mul_f32 v[82:83], v[82:83], v[96:97] op_sel_hi:[1,0]
	v_pk_mul_f32 v[80:81], v[80:81], v[96:97] op_sel_hi:[1,0]
	s_cbranch_vccnz .LBB0_973
	v_pk_mul_f32 v[96:97], v[94:95], v[94:95]
	v_pk_mul_f32 v[98:99], v[92:93], v[92:93]
	s_and_b64 s[38:39], s[40:41], exec
	v_pk_mov_b32 v[100:101], v[98:99], v[96:97] op_sel:[1,0]
	v_mov_b32_e32 v99, v97
	v_pk_add_f32 v[96:97], v[100:101], v[98:99]
	v_pk_mul_f32 v[98:99], v[90:91], v[90:91]
	v_pk_add_f32 v[96:97], v[96:97], v[96:97] op_sel_hi:[0,1]
	v_pk_mul_f32 v[100:101], v[88:89], v[88:89]
	v_mul_f32_e32 v96, v84, v84
	v_pk_mov_b32 v[102:103], v[100:101], v[98:99] op_sel:[1,0]
	v_mov_b32_e32 v101, v99
	v_pk_add_f32 v[98:99], v[102:103], v[100:101]
	v_pk_fma_f32 v[100:101], v[84:85], v[84:85], v[96:97] op_sel_hi:[1,1,0]
	v_mul_f32_e32 v96, v86, v86
	v_pk_add_f32 v[98:99], v[98:99], v[98:99] op_sel_hi:[0,1]
	v_pk_fma_f32 v[102:103], v[86:87], v[86:87], v[96:97] op_sel_hi:[1,1,0]
	v_mul_f32_e32 v100, v80, v80
	v_mul_f32_e32 v102, v81, v81
	v_mul_f32_e32 v96, v82, v82
	v_mul_f32_e32 v98, v83, v83
	v_pk_add_f32 v[100:101], v[100:101], v[102:103]
	v_pk_add_f32 v[96:97], v[96:97], v[98:99]
	s_cselect_b32 s39, s59, s61
	v_pk_add_f32 v[96:97], v[100:101], v[96:97]
	s_cselect_b32 s38, s58, s60
	v_add_f32_e32 v96, v96, v97
	v_mov_b32_e32 v97, v96
	v_pk_mul_f32 v[98:99], v[148:149], v[92:93]
	v_pk_mul_f32 v[106:107], v[146:147], v[88:89]
	s_waitcnt lgkmcnt(0)
	s_nop 1
	v_permlane16_swap_b32_e32 v96, v97
	v_add_f32_e32 v96, v96, v97
	v_mov_b32_e32 v97, v96
	s_nop 1
	v_permlane32_swap_b32_e32 v96, v97
	v_add_f32_e32 v96, v96, v97
	v_fmamk_f32 v96, v96, 0x3c800000, v182
	v_rsq_f32_e32 v100, v96
	v_lshlrev_b64 v[96:97], 11, v[172:173]
	v_lshl_add_u64 v[96:97], s[38:39], 0, v[96:97]
	s_lshl_b32 s38, s29, 1
	s_mov_b32 s39, s15
	v_lshl_add_u64 v[96:97], v[96:97], 0, s[38:39]
	v_lshl_add_u64 v[102:103], v[144:145], 1, v[96:97]
	v_pk_mul_f32 v[96:97], v[150:151], v[94:95]
	s_mov_b64 s[38:39], 0
	v_pk_mul_f32 v[104:105], v[96:97], v[100:101] op_sel_hi:[1,0]
	v_pk_mul_f32 v[96:97], v[98:99], v[100:101] op_sel_hi:[1,0]
	v_pk_mul_f32 v[98:99], v[152:153], v[90:91]
	v_cvt_pk_bf16_f32 v96, v96, v97
	v_pk_mul_f32 v[108:109], v[98:99], v[100:101] op_sel_hi:[1,0]
	v_pk_mul_f32 v[98:99], v[106:107], v[100:101] op_sel_hi:[1,0]
	v_cvt_pk_bf16_f32 v97, v104, v105
	v_cvt_pk_bf16_f32 v98, v98, v99
	v_cvt_pk_bf16_f32 v99, v108, v109
	global_store_dwordx4 v[102:103], v[96:99], off
	v_pk_mul_f32 v[106:107], v[154:155], v[80:81]
	s_nop 0
	v_pk_mul_f32 v[96:97], v[158:159], v[86:87]
	v_pk_mul_f32 v[98:99], v[156:157], v[84:85]
	v_pk_mul_f32 v[104:105], v[96:97], v[100:101] op_sel_hi:[1,0]
	v_pk_mul_f32 v[96:97], v[98:99], v[100:101] op_sel_hi:[1,0]
	v_pk_mul_f32 v[98:99], v[160:161], v[82:83]
	v_cvt_pk_bf16_f32 v96, v96, v97
	v_pk_mul_f32 v[108:109], v[98:99], v[100:101] op_sel_hi:[1,0]
	v_pk_mul_f32 v[98:99], v[106:107], v[100:101] op_sel_hi:[1,0]
	v_cvt_pk_bf16_f32 v97, v104, v105
	v_cvt_pk_bf16_f32 v98, v98, v99
	v_cvt_pk_bf16_f32 v99, v108, v109
	global_store_dwordx4 v[102:103], v[96:99], off offset:64

.LBB0_975:
	v_fmamk_f32 v80, v188, 0x3a800000, v182
	v_rsq_f32_e32 v80, v80
	s_and_b64 vcc, exec, s[6:7]
	s_mov_b64 s[38:39], -1
	v_pk_mul_f32 v[78:79], v[78:79], v[80:81] op_sel_hi:[1,0]
	v_pk_mul_f32 v[76:77], v[76:77], v[80:81] op_sel_hi:[1,0]
	v_pk_mul_f32 v[74:75], v[74:75], v[80:81] op_sel_hi:[1,0]
	v_pk_mul_f32 v[72:73], v[72:73], v[80:81] op_sel_hi:[1,0]
	v_pk_mul_f32 v[70:71], v[70:71], v[80:81] op_sel_hi:[1,0]
	v_pk_mul_f32 v[68:69], v[68:69], v[80:81] op_sel_hi:[1,0]
	v_pk_mul_f32 v[66:67], v[66:67], v[80:81] op_sel_hi:[1,0]
	v_pk_mul_f32 v[64:65], v[64:65], v[80:81] op_sel_hi:[1,0]
	s_cbranch_vccnz .LBB0_977
	v_pk_mul_f32 v[80:81], v[78:79], v[78:79]
	v_pk_mul_f32 v[82:83], v[76:77], v[76:77]
	s_and_b64 s[38:39], s[40:41], exec
	v_pk_mov_b32 v[84:85], v[82:83], v[80:81] op_sel:[1,0]
	v_mov_b32_e32 v83, v81
	v_pk_add_f32 v[80:81], v[84:85], v[82:83]
	v_pk_mul_f32 v[82:83], v[74:75], v[74:75]
	v_pk_add_f32 v[80:81], v[80:81], v[80:81] op_sel_hi:[0,1]
	v_pk_mul_f32 v[84:85], v[72:73], v[72:73]
	v_mul_f32_e32 v80, v68, v68
	v_pk_mov_b32 v[86:87], v[84:85], v[82:83] op_sel:[1,0]
	v_mov_b32_e32 v85, v83
	v_pk_add_f32 v[82:83], v[86:87], v[84:85]
	v_pk_fma_f32 v[84:85], v[68:69], v[68:69], v[80:81] op_sel_hi:[1,1,0]
	v_mul_f32_e32 v80, v70, v70
	v_pk_add_f32 v[82:83], v[82:83], v[82:83] op_sel_hi:[0,1]
	v_pk_fma_f32 v[86:87], v[70:71], v[70:71], v[80:81] op_sel_hi:[1,1,0]
	v_mul_f32_e32 v84, v64, v64
	v_mul_f32_e32 v86, v65, v65
	v_mul_f32_e32 v80, v66, v66
	v_mul_f32_e32 v82, v67, v67
	v_pk_add_f32 v[84:85], v[84:85], v[86:87]
	v_pk_add_f32 v[80:81], v[80:81], v[82:83]
	s_cselect_b32 s39, s59, s61
	v_pk_add_f32 v[80:81], v[84:85], v[80:81]
	s_cselect_b32 s38, s58, s60
	v_add_f32_e32 v80, v80, v81
	v_mov_b32_e32 v81, v80
	v_pk_mul_f32 v[82:83], v[148:149], v[76:77]
	v_pk_mul_f32 v[90:91], v[146:147], v[72:73]
	s_waitcnt lgkmcnt(0)
	s_nop 1
	v_permlane16_swap_b32_e32 v80, v81
	v_add_f32_e32 v80, v80, v81
	v_mov_b32_e32 v81, v80
	s_nop 1
	v_permlane32_swap_b32_e32 v80, v81
	v_add_f32_e32 v80, v80, v81
	v_fmamk_f32 v80, v80, 0x3c800000, v182
	v_rsq_f32_e32 v84, v80
	v_lshlrev_b64 v[80:81], 11, v[170:171]
	v_lshl_add_u64 v[80:81], s[38:39], 0, v[80:81]
	s_lshl_b32 s38, s29, 1
	s_mov_b32 s39, s15
	v_lshl_add_u64 v[80:81], v[80:81], 0, s[38:39]
	v_lshl_add_u64 v[86:87], v[144:145], 1, v[80:81]
	v_pk_mul_f32 v[80:81], v[150:151], v[78:79]
	s_mov_b64 s[38:39], 0
	v_pk_mul_f32 v[88:89], v[80:81], v[84:85] op_sel_hi:[1,0]
	v_pk_mul_f32 v[80:81], v[82:83], v[84:85] op_sel_hi:[1,0]
	v_pk_mul_f32 v[82:83], v[152:153], v[74:75]
	v_cvt_pk_bf16_f32 v80, v80, v81
	v_pk_mul_f32 v[92:93], v[82:83], v[84:85] op_sel_hi:[1,0]
	v_pk_mul_f32 v[82:83], v[90:91], v[84:85] op_sel_hi:[1,0]
	v_cvt_pk_bf16_f32 v81, v88, v89
	v_cvt_pk_bf16_f32 v82, v82, v83
	v_cvt_pk_bf16_f32 v83, v92, v93
	global_store_dwordx4 v[86:87], v[80:83], off
	v_pk_mul_f32 v[90:91], v[154:155], v[64:65]
	s_nop 0
	v_pk_mul_f32 v[80:81], v[158:159], v[70:71]
	v_pk_mul_f32 v[82:83], v[156:157], v[68:69]
	v_pk_mul_f32 v[88:89], v[80:81], v[84:85] op_sel_hi:[1,0]
	v_pk_mul_f32 v[80:81], v[82:83], v[84:85] op_sel_hi:[1,0]
	v_pk_mul_f32 v[82:83], v[160:161], v[66:67]
	v_cvt_pk_bf16_f32 v80, v80, v81
	v_pk_mul_f32 v[92:93], v[82:83], v[84:85] op_sel_hi:[1,0]
	v_pk_mul_f32 v[82:83], v[90:91], v[84:85] op_sel_hi:[1,0]
	v_cvt_pk_bf16_f32 v81, v88, v89
	v_cvt_pk_bf16_f32 v82, v82, v83
	v_cvt_pk_bf16_f32 v83, v92, v93
	global_store_dwordx4 v[86:87], v[80:83], off offset:64

.LBB0_979:
	v_fmamk_f32 v64, v187, 0x3a800000, v182
	v_rsq_f32_e32 v64, v64
	s_and_b64 vcc, exec, s[6:7]
	s_mov_b64 s[38:39], -1
	v_pk_mul_f32 v[62:63], v[62:63], v[64:65] op_sel_hi:[1,0]
	v_pk_mul_f32 v[60:61], v[60:61], v[64:65] op_sel_hi:[1,0]
	v_pk_mul_f32 v[58:59], v[58:59], v[64:65] op_sel_hi:[1,0]
	v_pk_mul_f32 v[56:57], v[56:57], v[64:65] op_sel_hi:[1,0]
	v_pk_mul_f32 v[54:55], v[54:55], v[64:65] op_sel_hi:[1,0]
	v_pk_mul_f32 v[52:53], v[52:53], v[64:65] op_sel_hi:[1,0]
	v_pk_mul_f32 v[50:51], v[50:51], v[64:65] op_sel_hi:[1,0]
	v_pk_mul_f32 v[48:49], v[48:49], v[64:65] op_sel_hi:[1,0]
	s_cbranch_vccnz .LBB0_981
	v_pk_mul_f32 v[64:65], v[62:63], v[62:63]
	v_pk_mul_f32 v[66:67], v[60:61], v[60:61]
	s_and_b64 s[38:39], s[40:41], exec
	v_pk_mov_b32 v[68:69], v[66:67], v[64:65] op_sel:[1,0]
	v_mov_b32_e32 v67, v65
	v_pk_add_f32 v[64:65], v[68:69], v[66:67]
	v_pk_mul_f32 v[66:67], v[58:59], v[58:59]
	v_pk_add_f32 v[64:65], v[64:65], v[64:65] op_sel_hi:[0,1]
	v_pk_mul_f32 v[68:69], v[56:57], v[56:57]
	v_mul_f32_e32 v64, v52, v52
	v_pk_mov_b32 v[70:71], v[68:69], v[66:67] op_sel:[1,0]
	v_mov_b32_e32 v69, v67
	v_pk_add_f32 v[66:67], v[70:71], v[68:69]
	v_pk_fma_f32 v[68:69], v[52:53], v[52:53], v[64:65] op_sel_hi:[1,1,0]
	v_mul_f32_e32 v64, v54, v54
	v_pk_add_f32 v[66:67], v[66:67], v[66:67] op_sel_hi:[0,1]
	v_pk_fma_f32 v[70:71], v[54:55], v[54:55], v[64:65] op_sel_hi:[1,1,0]
	v_mul_f32_e32 v68, v48, v48
	v_mul_f32_e32 v70, v49, v49
	v_mul_f32_e32 v64, v50, v50
	v_mul_f32_e32 v66, v51, v51
	v_pk_add_f32 v[68:69], v[68:69], v[70:71]
	v_pk_add_f32 v[64:65], v[64:65], v[66:67]
	s_cselect_b32 s39, s59, s61
	v_pk_add_f32 v[64:65], v[68:69], v[64:65]
	s_cselect_b32 s38, s58, s60
	v_add_f32_e32 v64, v64, v65
	v_mov_b32_e32 v65, v64
	v_pk_mul_f32 v[66:67], v[148:149], v[60:61]
	v_pk_mul_f32 v[74:75], v[146:147], v[56:57]
	s_waitcnt lgkmcnt(0)
	s_nop 1
	v_permlane16_swap_b32_e32 v64, v65
	v_add_f32_e32 v64, v64, v65
	v_mov_b32_e32 v65, v64
	s_nop 1
	v_permlane32_swap_b32_e32 v64, v65
	v_add_f32_e32 v64, v64, v65
	v_fmamk_f32 v64, v64, 0x3c800000, v182
	v_rsq_f32_e32 v68, v64
	v_lshlrev_b64 v[64:65], 11, v[168:169]
	v_lshl_add_u64 v[64:65], s[38:39], 0, v[64:65]
	s_lshl_b32 s38, s29, 1
	s_mov_b32 s39, s15
	v_lshl_add_u64 v[64:65], v[64:65], 0, s[38:39]
	v_lshl_add_u64 v[70:71], v[144:145], 1, v[64:65]
	v_pk_mul_f32 v[64:65], v[150:151], v[62:63]
	s_mov_b64 s[38:39], 0
	v_pk_mul_f32 v[72:73], v[64:65], v[68:69] op_sel_hi:[1,0]
	v_pk_mul_f32 v[64:65], v[66:67], v[68:69] op_sel_hi:[1,0]
	v_pk_mul_f32 v[66:67], v[152:153], v[58:59]
	v_cvt_pk_bf16_f32 v64, v64, v65
	v_pk_mul_f32 v[76:77], v[66:67], v[68:69] op_sel_hi:[1,0]
	v_pk_mul_f32 v[66:67], v[74:75], v[68:69] op_sel_hi:[1,0]
	v_cvt_pk_bf16_f32 v65, v72, v73
	v_cvt_pk_bf16_f32 v66, v66, v67
	v_cvt_pk_bf16_f32 v67, v76, v77
	global_store_dwordx4 v[70:71], v[64:67], off
	v_pk_mul_f32 v[74:75], v[154:155], v[48:49]
	s_nop 0
	v_pk_mul_f32 v[64:65], v[158:159], v[54:55]
	v_pk_mul_f32 v[66:67], v[156:157], v[52:53]
	v_pk_mul_f32 v[72:73], v[64:65], v[68:69] op_sel_hi:[1,0]
	v_pk_mul_f32 v[64:65], v[66:67], v[68:69] op_sel_hi:[1,0]
	v_pk_mul_f32 v[66:67], v[160:161], v[50:51]
	v_cvt_pk_bf16_f32 v64, v64, v65
	v_pk_mul_f32 v[76:77], v[66:67], v[68:69] op_sel_hi:[1,0]
	v_pk_mul_f32 v[66:67], v[74:75], v[68:69] op_sel_hi:[1,0]
	v_cvt_pk_bf16_f32 v65, v72, v73
	v_cvt_pk_bf16_f32 v66, v66, v67
	v_cvt_pk_bf16_f32 v67, v76, v77
	global_store_dwordx4 v[70:71], v[64:67], off offset:64

.LBB0_983:
	v_fmamk_f32 v48, v186, 0x3a800000, v182
	v_rsq_f32_e32 v48, v48
	s_and_b64 vcc, exec, s[6:7]
	s_mov_b64 s[38:39], -1
	v_pk_mul_f32 v[46:47], v[46:47], v[48:49] op_sel_hi:[1,0]
	v_pk_mul_f32 v[44:45], v[44:45], v[48:49] op_sel_hi:[1,0]
	v_pk_mul_f32 v[42:43], v[42:43], v[48:49] op_sel_hi:[1,0]
	v_pk_mul_f32 v[40:41], v[40:41], v[48:49] op_sel_hi:[1,0]
	v_pk_mul_f32 v[38:39], v[38:39], v[48:49] op_sel_hi:[1,0]
	v_pk_mul_f32 v[36:37], v[36:37], v[48:49] op_sel_hi:[1,0]
	v_pk_mul_f32 v[34:35], v[34:35], v[48:49] op_sel_hi:[1,0]
	v_pk_mul_f32 v[32:33], v[32:33], v[48:49] op_sel_hi:[1,0]
	s_cbranch_vccnz .LBB0_985
	v_pk_mul_f32 v[48:49], v[46:47], v[46:47]
	v_pk_mul_f32 v[50:51], v[44:45], v[44:45]
	s_and_b64 s[38:39], s[40:41], exec
	v_pk_mov_b32 v[52:53], v[50:51], v[48:49] op_sel:[1,0]
	v_mov_b32_e32 v51, v49
	v_pk_add_f32 v[48:49], v[52:53], v[50:51]
	v_pk_mul_f32 v[50:51], v[42:43], v[42:43]
	v_pk_add_f32 v[48:49], v[48:49], v[48:49] op_sel_hi:[0,1]
	v_pk_mul_f32 v[52:53], v[40:41], v[40:41]
	v_mul_f32_e32 v48, v36, v36
	v_pk_mov_b32 v[54:55], v[52:53], v[50:51] op_sel:[1,0]
	v_mov_b32_e32 v53, v51
	v_pk_add_f32 v[50:51], v[54:55], v[52:53]
	v_pk_fma_f32 v[52:53], v[36:37], v[36:37], v[48:49] op_sel_hi:[1,1,0]
	v_mul_f32_e32 v48, v38, v38
	v_pk_add_f32 v[50:51], v[50:51], v[50:51] op_sel_hi:[0,1]
	v_pk_fma_f32 v[54:55], v[38:39], v[38:39], v[48:49] op_sel_hi:[1,1,0]
	v_mul_f32_e32 v52, v32, v32
	v_mul_f32_e32 v54, v33, v33
	v_mul_f32_e32 v48, v34, v34
	v_mul_f32_e32 v50, v35, v35
	v_pk_add_f32 v[52:53], v[52:53], v[54:55]
	v_pk_add_f32 v[48:49], v[48:49], v[50:51]
	s_cselect_b32 s39, s59, s61
	v_pk_add_f32 v[48:49], v[52:53], v[48:49]
	s_cselect_b32 s38, s58, s60
	v_add_f32_e32 v48, v48, v49
	v_mov_b32_e32 v49, v48
	v_pk_mul_f32 v[50:51], v[148:149], v[44:45]
	v_pk_mul_f32 v[58:59], v[146:147], v[40:41]
	s_waitcnt lgkmcnt(0)
	s_nop 1
	v_permlane16_swap_b32_e32 v48, v49
	v_add_f32_e32 v48, v48, v49
	v_mov_b32_e32 v49, v48
	s_nop 1
	v_permlane32_swap_b32_e32 v48, v49
	v_add_f32_e32 v48, v48, v49
	v_fmamk_f32 v48, v48, 0x3c800000, v182
	v_rsq_f32_e32 v52, v48
	v_lshlrev_b64 v[48:49], 11, v[166:167]
	v_lshl_add_u64 v[48:49], s[38:39], 0, v[48:49]
	s_lshl_b32 s38, s29, 1
	s_mov_b32 s39, s15
	v_lshl_add_u64 v[48:49], v[48:49], 0, s[38:39]
	v_lshl_add_u64 v[54:55], v[144:145], 1, v[48:49]
	v_pk_mul_f32 v[48:49], v[150:151], v[46:47]
	s_mov_b64 s[38:39], 0
	v_pk_mul_f32 v[56:57], v[48:49], v[52:53] op_sel_hi:[1,0]
	v_pk_mul_f32 v[48:49], v[50:51], v[52:53] op_sel_hi:[1,0]
	v_pk_mul_f32 v[50:51], v[152:153], v[42:43]
	v_cvt_pk_bf16_f32 v48, v48, v49
	v_pk_mul_f32 v[60:61], v[50:51], v[52:53] op_sel_hi:[1,0]
	v_pk_mul_f32 v[50:51], v[58:59], v[52:53] op_sel_hi:[1,0]
	v_cvt_pk_bf16_f32 v49, v56, v57
	v_cvt_pk_bf16_f32 v50, v50, v51
	v_cvt_pk_bf16_f32 v51, v60, v61
	global_store_dwordx4 v[54:55], v[48:51], off
	v_pk_mul_f32 v[58:59], v[154:155], v[32:33]
	s_nop 0
	v_pk_mul_f32 v[48:49], v[158:159], v[38:39]
	v_pk_mul_f32 v[50:51], v[156:157], v[36:37]
	v_pk_mul_f32 v[56:57], v[48:49], v[52:53] op_sel_hi:[1,0]
	v_pk_mul_f32 v[48:49], v[50:51], v[52:53] op_sel_hi:[1,0]
	v_pk_mul_f32 v[50:51], v[160:161], v[34:35]
	v_cvt_pk_bf16_f32 v48, v48, v49
	v_pk_mul_f32 v[60:61], v[50:51], v[52:53] op_sel_hi:[1,0]
	v_pk_mul_f32 v[50:51], v[58:59], v[52:53] op_sel_hi:[1,0]
	v_cvt_pk_bf16_f32 v49, v56, v57
	v_cvt_pk_bf16_f32 v50, v50, v51
	v_cvt_pk_bf16_f32 v51, v60, v61
	global_store_dwordx4 v[54:55], v[48:51], off offset:64

.LBB0_987:
	v_fmamk_f32 v32, v185, 0x3a800000, v182
	v_rsq_f32_e32 v32, v32
	s_and_b64 vcc, exec, s[6:7]
	s_mov_b64 s[38:39], -1
	v_pk_mul_f32 v[30:31], v[30:31], v[32:33] op_sel_hi:[1,0]
	v_pk_mul_f32 v[28:29], v[28:29], v[32:33] op_sel_hi:[1,0]
	v_pk_mul_f32 v[26:27], v[26:27], v[32:33] op_sel_hi:[1,0]
	v_pk_mul_f32 v[24:25], v[24:25], v[32:33] op_sel_hi:[1,0]
	v_pk_mul_f32 v[22:23], v[22:23], v[32:33] op_sel_hi:[1,0]
	v_pk_mul_f32 v[20:21], v[20:21], v[32:33] op_sel_hi:[1,0]
	v_pk_mul_f32 v[18:19], v[18:19], v[32:33] op_sel_hi:[1,0]
	v_pk_mul_f32 v[16:17], v[16:17], v[32:33] op_sel_hi:[1,0]
	s_cbranch_vccnz .LBB0_989
	v_pk_mul_f32 v[32:33], v[30:31], v[30:31]
	v_pk_mul_f32 v[34:35], v[28:29], v[28:29]
	s_and_b64 s[38:39], s[40:41], exec
	v_pk_mov_b32 v[36:37], v[34:35], v[32:33] op_sel:[1,0]
	v_mov_b32_e32 v35, v33
	v_pk_add_f32 v[32:33], v[36:37], v[34:35]
	v_pk_mul_f32 v[34:35], v[26:27], v[26:27]
	v_pk_add_f32 v[32:33], v[32:33], v[32:33] op_sel_hi:[0,1]
	v_pk_mul_f32 v[36:37], v[24:25], v[24:25]
	v_mul_f32_e32 v32, v20, v20
	v_pk_mov_b32 v[38:39], v[36:37], v[34:35] op_sel:[1,0]
	v_mov_b32_e32 v37, v35
	v_pk_add_f32 v[34:35], v[38:39], v[36:37]
	v_pk_fma_f32 v[36:37], v[20:21], v[20:21], v[32:33] op_sel_hi:[1,1,0]
	v_mul_f32_e32 v32, v22, v22
	v_pk_add_f32 v[34:35], v[34:35], v[34:35] op_sel_hi:[0,1]
	v_pk_fma_f32 v[38:39], v[22:23], v[22:23], v[32:33] op_sel_hi:[1,1,0]
	v_mul_f32_e32 v36, v16, v16
	v_mul_f32_e32 v38, v17, v17
	v_mul_f32_e32 v32, v18, v18
	v_mul_f32_e32 v34, v19, v19
	v_pk_add_f32 v[36:37], v[36:37], v[38:39]
	v_pk_add_f32 v[32:33], v[32:33], v[34:35]
	s_cselect_b32 s39, s59, s61
	v_pk_add_f32 v[32:33], v[36:37], v[32:33]
	s_cselect_b32 s38, s58, s60
	v_add_f32_e32 v32, v32, v33
	v_mov_b32_e32 v33, v32
	v_pk_mul_f32 v[34:35], v[148:149], v[28:29]
	v_pk_mul_f32 v[42:43], v[146:147], v[24:25]
	s_waitcnt lgkmcnt(0)
	s_nop 1
	v_permlane16_swap_b32_e32 v32, v33
	v_add_f32_e32 v32, v32, v33
	v_mov_b32_e32 v33, v32
	s_nop 1
	v_permlane32_swap_b32_e32 v32, v33
	v_add_f32_e32 v32, v32, v33
	v_fmamk_f32 v32, v32, 0x3c800000, v182
	v_rsq_f32_e32 v36, v32
	v_lshlrev_b64 v[32:33], 11, v[164:165]
	v_lshl_add_u64 v[32:33], s[38:39], 0, v[32:33]
	s_lshl_b32 s38, s29, 1
	s_mov_b32 s39, s15
	v_lshl_add_u64 v[32:33], v[32:33], 0, s[38:39]
	v_lshl_add_u64 v[38:39], v[144:145], 1, v[32:33]
	v_pk_mul_f32 v[32:33], v[150:151], v[30:31]
	s_mov_b64 s[38:39], 0
	v_pk_mul_f32 v[40:41], v[32:33], v[36:37] op_sel_hi:[1,0]
	v_pk_mul_f32 v[32:33], v[34:35], v[36:37] op_sel_hi:[1,0]
	v_pk_mul_f32 v[34:35], v[152:153], v[26:27]
	v_cvt_pk_bf16_f32 v32, v32, v33
	v_pk_mul_f32 v[44:45], v[34:35], v[36:37] op_sel_hi:[1,0]
	v_pk_mul_f32 v[34:35], v[42:43], v[36:37] op_sel_hi:[1,0]
	v_cvt_pk_bf16_f32 v33, v40, v41
	v_cvt_pk_bf16_f32 v34, v34, v35
	v_cvt_pk_bf16_f32 v35, v44, v45
	global_store_dwordx4 v[38:39], v[32:35], off
	v_pk_mul_f32 v[42:43], v[154:155], v[16:17]
	s_nop 0
	v_pk_mul_f32 v[32:33], v[158:159], v[22:23]
	v_pk_mul_f32 v[34:35], v[156:157], v[20:21]
	v_pk_mul_f32 v[40:41], v[32:33], v[36:37] op_sel_hi:[1,0]
	v_pk_mul_f32 v[32:33], v[34:35], v[36:37] op_sel_hi:[1,0]
	v_pk_mul_f32 v[34:35], v[160:161], v[18:19]
	v_cvt_pk_bf16_f32 v32, v32, v33
	v_pk_mul_f32 v[44:45], v[34:35], v[36:37] op_sel_hi:[1,0]
	v_pk_mul_f32 v[34:35], v[42:43], v[36:37] op_sel_hi:[1,0]
	v_cvt_pk_bf16_f32 v33, v40, v41
	v_cvt_pk_bf16_f32 v34, v34, v35
	v_cvt_pk_bf16_f32 v35, v44, v45
	global_store_dwordx4 v[38:39], v[32:35], off offset:64

.LBB0_991:
	v_fmamk_f32 v16, v184, 0x3a800000, v182
	v_rsq_f32_e32 v16, v16
	s_and_b64 vcc, exec, s[6:7]
	s_mov_b64 s[6:7], -1
	v_pk_mul_f32 v[14:15], v[14:15], v[16:17] op_sel_hi:[1,0]
	v_pk_mul_f32 v[12:13], v[12:13], v[16:17] op_sel_hi:[1,0]
	v_pk_mul_f32 v[10:11], v[10:11], v[16:17] op_sel_hi:[1,0]
	v_pk_mul_f32 v[8:9], v[8:9], v[16:17] op_sel_hi:[1,0]
	v_pk_mul_f32 v[6:7], v[6:7], v[16:17] op_sel_hi:[1,0]
	v_pk_mul_f32 v[4:5], v[4:5], v[16:17] op_sel_hi:[1,0]
	v_pk_mul_f32 v[2:3], v[2:3], v[16:17] op_sel_hi:[1,0]
	v_pk_mul_f32 v[0:1], v[0:1], v[16:17] op_sel_hi:[1,0]
	s_cbranch_vccnz .LBB0_993
	v_pk_mul_f32 v[16:17], v[14:15], v[14:15]
	v_pk_mul_f32 v[18:19], v[12:13], v[12:13]
	s_and_b64 s[6:7], s[40:41], exec
	v_pk_mov_b32 v[20:21], v[18:19], v[16:17] op_sel:[1,0]
	v_mov_b32_e32 v19, v17
	v_pk_add_f32 v[16:17], v[20:21], v[18:19]
	v_pk_mul_f32 v[18:19], v[10:11], v[10:11]
	v_pk_add_f32 v[16:17], v[16:17], v[16:17] op_sel_hi:[0,1]
	v_pk_mul_f32 v[20:21], v[8:9], v[8:9]
	v_mul_f32_e32 v16, v4, v4
	v_pk_mov_b32 v[22:23], v[20:21], v[18:19] op_sel:[1,0]
	v_mov_b32_e32 v21, v19
	v_pk_add_f32 v[18:19], v[22:23], v[20:21]
	v_pk_fma_f32 v[20:21], v[4:5], v[4:5], v[16:17] op_sel_hi:[1,1,0]
	v_mul_f32_e32 v16, v6, v6
	v_pk_add_f32 v[18:19], v[18:19], v[18:19] op_sel_hi:[0,1]
	v_pk_fma_f32 v[22:23], v[6:7], v[6:7], v[16:17] op_sel_hi:[1,1,0]
	v_mul_f32_e32 v20, v0, v0
	v_mul_f32_e32 v22, v1, v1
	v_mul_f32_e32 v16, v2, v2
	v_mul_f32_e32 v18, v3, v3
	v_pk_add_f32 v[20:21], v[20:21], v[22:23]
	v_pk_add_f32 v[16:17], v[16:17], v[18:19]
	s_cselect_b32 s7, s59, s61
	v_pk_add_f32 v[16:17], v[20:21], v[16:17]
	s_cselect_b32 s6, s58, s60
	v_add_f32_e32 v16, v16, v17
	v_mov_b32_e32 v17, v16
	v_pk_mul_f32 v[18:19], v[148:149], v[12:13]
	v_pk_mul_f32 v[26:27], v[146:147], v[8:9]
	s_waitcnt lgkmcnt(0)
	s_nop 1
	v_permlane16_swap_b32_e32 v16, v17
	v_add_f32_e32 v16, v16, v17
	v_mov_b32_e32 v17, v16
	s_nop 1
	v_permlane32_swap_b32_e32 v16, v17
	v_add_f32_e32 v16, v16, v17
	v_fmamk_f32 v16, v16, 0x3c800000, v182
	v_rsq_f32_e32 v20, v16
	v_lshlrev_b64 v[16:17], 11, v[162:163]
	v_lshl_add_u64 v[16:17], s[6:7], 0, v[16:17]
	s_lshl_b32 s6, s29, 1
	s_mov_b32 s7, s15
	v_lshl_add_u64 v[16:17], v[16:17], 0, s[6:7]
	v_lshl_add_u64 v[22:23], v[144:145], 1, v[16:17]
	v_pk_mul_f32 v[16:17], v[150:151], v[14:15]
	s_mov_b64 s[6:7], 0
	v_pk_mul_f32 v[24:25], v[16:17], v[20:21] op_sel_hi:[1,0]
	v_pk_mul_f32 v[16:17], v[18:19], v[20:21] op_sel_hi:[1,0]
	v_pk_mul_f32 v[18:19], v[152:153], v[10:11]
	v_cvt_pk_bf16_f32 v16, v16, v17
	v_pk_mul_f32 v[28:29], v[18:19], v[20:21] op_sel_hi:[1,0]
	v_pk_mul_f32 v[18:19], v[26:27], v[20:21] op_sel_hi:[1,0]
	v_cvt_pk_bf16_f32 v17, v24, v25
	v_cvt_pk_bf16_f32 v18, v18, v19
	v_cvt_pk_bf16_f32 v19, v28, v29
	global_store_dwordx4 v[22:23], v[16:19], off
	v_pk_mul_f32 v[26:27], v[154:155], v[0:1]
	s_nop 0
	v_pk_mul_f32 v[16:17], v[158:159], v[6:7]
	v_pk_mul_f32 v[18:19], v[156:157], v[4:5]
	v_pk_mul_f32 v[24:25], v[16:17], v[20:21] op_sel_hi:[1,0]
	v_pk_mul_f32 v[16:17], v[18:19], v[20:21] op_sel_hi:[1,0]
	v_pk_mul_f32 v[18:19], v[160:161], v[2:3]
	v_cvt_pk_bf16_f32 v16, v16, v17
	v_pk_mul_f32 v[28:29], v[18:19], v[20:21] op_sel_hi:[1,0]
	v_pk_mul_f32 v[18:19], v[26:27], v[20:21] op_sel_hi:[1,0]
	v_cvt_pk_bf16_f32 v17, v24, v25
	v_cvt_pk_bf16_f32 v18, v18, v19
	v_cvt_pk_bf16_f32 v19, v28, v29
	global_store_dwordx4 v[22:23], v[16:19], off offset:64

.Lalign_4:
	s_waitcnt vmcnt(0)
	v_lshlrev_b32_e32 v246, 16, v236
	v_and_b32_e32 v247, 0xffff0000, v236
	v_lshlrev_b32_e32 v236, 16, v237
	v_and_b32_e32 v237, 0xffff0000, v237
	v_lshlrev_b32_e32 v248, 16, v238
	v_and_b32_e32 v249, 0xffff0000, v238
	v_lshlrev_b32_e32 v238, 16, v239
	v_and_b32_e32 v239, 0xffff0000, v239
	v_pk_add_f32 v[130:131], v[130:131], v[236:237]
	v_pk_add_f32 v[128:129], v[128:129], v[246:247]
	v_pk_add_f32 v[236:237], v[126:127], v[238:239]
	v_pk_add_f32 v[238:239], v[124:125], v[248:249]
	v_cvt_pk_bf16_f32 v124, v128, v129
	v_cvt_pk_bf16_f32 v125, v130, v131
	v_cvt_pk_bf16_f32 v126, v238, v239
	v_cvt_pk_bf16_f32 v127, v236, v237
	v_mul_f32_e32 v129, v129, v129
	v_mul_f32_e32 v131, v131, v131
	v_mul_f32_e32 v239, v239, v239
	v_mul_f32_e32 v237, v237, v237
	v_fmac_f32_e32 v129, v128, v128
	v_fmac_f32_e32 v131, v130, v130
	v_fmac_f32_e32 v239, v238, v238
	v_fmac_f32_e32 v237, v236, v236
	v_lshlrev_b32_e32 v250, 16, v240
	v_and_b32_e32 v251, 0xffff0000, v240
	global_store_dwordx4 v[244:245], v[124:127], off
	v_lshlrev_b32_e32 v240, 16, v241
	v_and_b32_e32 v241, 0xffff0000, v241
	v_add_f32_e32 v124, v129, v131
	v_add_f32_e32 v125, v239, v237
	v_add_f32_e32 v128, v124, v125
	v_lshlrev_b32_e32 v124, 16, v242
	v_and_b32_e32 v125, 0xffff0000, v242
	v_lshlrev_b32_e32 v126, 16, v243
	v_and_b32_e32 v127, 0xffff0000, v243
	v_pk_add_f32 v[116:117], v[116:117], v[250:251]
	v_pk_add_f32 v[118:119], v[118:119], v[240:241]
	v_pk_add_f32 v[126:127], v[114:115], v[126:127]
	v_pk_add_f32 v[114:115], v[112:113], v[124:125]
	v_mul_f32_e32 v113, v117, v117
	v_cvt_pk_bf16_f32 v112, v116, v117
	v_fmac_f32_e32 v113, v116, v116
	v_mul_f32_e32 v116, v119, v119
	v_fmac_f32_e32 v116, v118, v118
	v_add_f32_e32 v113, v113, v116
	v_mul_f32_e32 v116, v115, v115
	v_mul_f32_e32 v117, v127, v127
	v_fmac_f32_e32 v116, v114, v114
	v_fmac_f32_e32 v117, v126, v126
	v_add_f32_e32 v116, v116, v117
	v_add_f32_e32 v113, v113, v116
	v_add_f32_e32 v116, v128, v113
	v_mov_b32_e32 v117, v116
	v_cvt_pk_bf16_f32 v113, v118, v119
	v_cvt_pk_bf16_f32 v114, v114, v115
	v_cvt_pk_bf16_f32 v115, v126, v127
	global_store_dwordx4 v[244:245], v[112:115], off offset:256
	s_waitcnt lgkmcnt(0)
	s_nop 0
	s_nop 1
	v_permlane16_swap_b32_e32 v116, v117
	v_add_f32_e32 v112, v116, v117
	v_mov_b32_e32 v113, v112
	s_nop 1
	v_permlane32_swap_b32_e32 v112, v113
	s_and_saveexec_b64 s[36:37], vcc
	s_cbranch_execz .LBB0_1151
	v_lshl_add_u64 v[114:115], v[228:229], 2, s[14:15]
	v_add_f32_e32 v112, v112, v113
	global_atomic_add_f32 v[114:115], v112, off
.LBB0_1151:
	s_or_b64 exec, exec, s[36:37]
	s_or_b64 s[30:31], s[30:31], s[16:17]
	v_lshlrev_b32_e32 v114, 16, v180
	v_and_b32_e32 v115, 0xffff0000, v180
	v_lshlrev_b32_e32 v116, 16, v181
	v_and_b32_e32 v117, 0xffff0000, v181
	v_lshlrev_b32_e32 v118, 16, v182
	v_and_b32_e32 v119, 0xffff0000, v182
	v_lshlrev_b32_e32 v124, 16, v183
	v_and_b32_e32 v125, 0xffff0000, v183
	v_lshl_add_u64 v[112:113], s[30:31], 0, v[226:227]
	v_pk_add_f32 v[110:111], v[110:111], v[116:117]
	v_pk_add_f32 v[108:109], v[108:109], v[114:115]
	v_pk_add_f32 v[114:115], v[106:107], v[124:125]
	v_pk_add_f32 v[116:117], v[104:105], v[118:119]
	v_lshl_add_u64 v[104:105], s[12:13], 0, v[230:231]
	v_lshl_add_u64 v[118:119], v[112:113], 1, v[104:105]
	v_cvt_pk_bf16_f32 v104, v108, v109
	v_cvt_pk_bf16_f32 v105, v110, v111
	v_cvt_pk_bf16_f32 v106, v116, v117
	v_cvt_pk_bf16_f32 v107, v114, v115
	global_store_dwordx4 v[118:119], v[104:107], off
	s_nop 1
	v_mul_f32_e32 v104, v109, v109
	v_mul_f32_e32 v105, v111, v111
	v_fmac_f32_e32 v104, v108, v108
	v_fmac_f32_e32 v105, v110, v110
	v_add_f32_e32 v104, v104, v105
	v_mul_f32_e32 v105, v117, v117
	v_mul_f32_e32 v106, v115, v115
	v_fmac_f32_e32 v105, v116, v116
	v_fmac_f32_e32 v106, v114, v114
	v_add_f32_e32 v105, v105, v106
	v_add_f32_e32 v114, v104, v105
	v_lshlrev_b32_e32 v104, 16, v176
	v_and_b32_e32 v105, 0xffff0000, v176
	v_lshlrev_b32_e32 v106, 16, v177
	v_and_b32_e32 v107, 0xffff0000, v177
	v_lshlrev_b32_e32 v108, 16, v178
	v_and_b32_e32 v109, 0xffff0000, v178
	v_lshlrev_b32_e32 v110, 16, v179
	v_and_b32_e32 v111, 0xffff0000, v179
	v_pk_add_f32 v[100:101], v[100:101], v[104:105]
	v_pk_add_f32 v[102:103], v[102:103], v[106:107]
	v_pk_add_f32 v[104:105], v[98:99], v[110:111]
	v_pk_add_f32 v[98:99], v[96:97], v[108:109]
	v_mul_f32_e32 v97, v101, v101
	v_cvt_pk_bf16_f32 v96, v100, v101
	v_fmac_f32_e32 v97, v100, v100
	v_mul_f32_e32 v100, v103, v103
	v_fmac_f32_e32 v100, v102, v102
	v_add_f32_e32 v97, v97, v100
	v_mul_f32_e32 v100, v99, v99
	v_mul_f32_e32 v101, v105, v105
	v_fmac_f32_e32 v100, v98, v98
	v_fmac_f32_e32 v101, v104, v104
	v_add_f32_e32 v100, v100, v101
	v_add_f32_e32 v97, v97, v100
	v_add_f32_e32 v100, v114, v97
	v_mov_b32_e32 v101, v100
	v_cvt_pk_bf16_f32 v97, v102, v103
	v_cvt_pk_bf16_f32 v98, v98, v99
	v_cvt_pk_bf16_f32 v99, v104, v105
	global_store_dwordx4 v[118:119], v[96:99], off offset:256
	s_waitcnt lgkmcnt(0)
	s_nop 0
	s_nop 1
	v_permlane16_swap_b32_e32 v100, v101
	v_add_f32_e32 v96, v100, v101
	v_mov_b32_e32 v97, v96
	s_nop 1
	v_permlane32_swap_b32_e32 v96, v97
	s_and_saveexec_b64 s[30:31], vcc
	s_cbranch_execz .LBB0_1153
	v_lshl_add_u64 v[98:99], v[222:223], 2, s[14:15]
	v_add_f32_e32 v96, v96, v97
	global_atomic_add_f32 v[98:99], v96, off
.LBB0_1153:
	s_or_b64 exec, exec, s[30:31]
	v_lshlrev_b32_e32 v96, 16, v172
	v_and_b32_e32 v97, 0xffff0000, v172
	v_lshlrev_b32_e32 v98, 16, v173
	v_and_b32_e32 v99, 0xffff0000, v173
	v_lshlrev_b32_e32 v100, 16, v174
	v_and_b32_e32 v101, 0xffff0000, v174
	v_lshlrev_b32_e32 v102, 16, v175
	v_and_b32_e32 v103, 0xffff0000, v175
	v_pk_add_f32 v[94:95], v[94:95], v[98:99]
	v_pk_add_f32 v[92:93], v[92:93], v[96:97]
	v_pk_add_f32 v[96:97], v[90:91], v[102:103]
	v_pk_add_f32 v[98:99], v[88:89], v[100:101]
	v_lshl_add_u64 v[88:89], s[12:13], 0, v[224:225]
	v_lshl_add_u64 v[100:101], v[112:113], 1, v[88:89]
	v_cvt_pk_bf16_f32 v88, v92, v93
	v_cvt_pk_bf16_f32 v89, v94, v95
	v_cvt_pk_bf16_f32 v90, v98, v99
	v_cvt_pk_bf16_f32 v91, v96, v97
	global_store_dwordx4 v[100:101], v[88:91], off
	s_nop 1
	v_mul_f32_e32 v88, v93, v93
	v_mul_f32_e32 v89, v95, v95
	v_fmac_f32_e32 v88, v92, v92
	v_fmac_f32_e32 v89, v94, v94
	v_add_f32_e32 v88, v88, v89
	v_mul_f32_e32 v89, v99, v99
	v_mul_f32_e32 v90, v97, v97
	v_fmac_f32_e32 v89, v98, v98
	v_fmac_f32_e32 v90, v96, v96
	v_add_f32_e32 v89, v89, v90
	v_add_f32_e32 v96, v88, v89
	v_lshlrev_b32_e32 v88, 16, v168
	v_and_b32_e32 v89, 0xffff0000, v168
	v_lshlrev_b32_e32 v90, 16, v169
	v_and_b32_e32 v91, 0xffff0000, v169
	v_lshlrev_b32_e32 v92, 16, v170
	v_and_b32_e32 v93, 0xffff0000, v170
	v_lshlrev_b32_e32 v94, 16, v171
	v_and_b32_e32 v95, 0xffff0000, v171
	v_pk_add_f32 v[84:85], v[84:85], v[88:89]
	v_pk_add_f32 v[86:87], v[86:87], v[90:91]
	v_pk_add_f32 v[88:89], v[82:83], v[94:95]
	v_pk_add_f32 v[82:83], v[80:81], v[92:93]
	v_mul_f32_e32 v81, v85, v85
	v_cvt_pk_bf16_f32 v80, v84, v85
	v_fmac_f32_e32 v81, v84, v84
	v_mul_f32_e32 v84, v87, v87
	v_fmac_f32_e32 v84, v86, v86
	v_add_f32_e32 v81, v81, v84
	v_mul_f32_e32 v84, v83, v83
	v_mul_f32_e32 v85, v89, v89
	v_fmac_f32_e32 v84, v82, v82
	v_fmac_f32_e32 v85, v88, v88
	v_add_f32_e32 v84, v84, v85
	v_add_f32_e32 v81, v81, v84
	v_add_f32_e32 v84, v96, v81
	v_mov_b32_e32 v85, v84
	v_cvt_pk_bf16_f32 v81, v86, v87
	v_cvt_pk_bf16_f32 v82, v82, v83
	v_cvt_pk_bf16_f32 v83, v88, v89
	global_store_dwordx4 v[100:101], v[80:83], off offset:256
	s_waitcnt lgkmcnt(0)
	s_nop 0
	s_nop 1
	v_permlane16_swap_b32_e32 v84, v85
	v_add_f32_e32 v80, v84, v85
	v_mov_b32_e32 v81, v80
	s_nop 1
	v_permlane32_swap_b32_e32 v80, v81
	s_and_saveexec_b64 s[30:31], vcc
	s_cbranch_execz .LBB0_1155
	v_lshl_add_u64 v[82:83], v[218:219], 2, s[14:15]
	v_add_f32_e32 v80, v80, v81
	global_atomic_add_f32 v[82:83], v80, off
.LBB0_1155:
	s_or_b64 exec, exec, s[30:31]
	v_lshlrev_b32_e32 v80, 16, v164
	v_and_b32_e32 v81, 0xffff0000, v164
	v_lshlrev_b32_e32 v82, 16, v165
	v_and_b32_e32 v83, 0xffff0000, v165
	v_lshlrev_b32_e32 v84, 16, v166
	v_and_b32_e32 v85, 0xffff0000, v166
	v_lshlrev_b32_e32 v86, 16, v167
	v_and_b32_e32 v87, 0xffff0000, v167
	v_pk_add_f32 v[78:79], v[78:79], v[82:83]
	v_pk_add_f32 v[76:77], v[76:77], v[80:81]
	v_pk_add_f32 v[80:81], v[74:75], v[86:87]
	v_pk_add_f32 v[82:83], v[72:73], v[84:85]
	v_lshl_add_u64 v[72:73], s[12:13], 0, v[220:221]
	v_lshl_add_u64 v[84:85], v[112:113], 1, v[72:73]
	v_cvt_pk_bf16_f32 v72, v76, v77
	v_cvt_pk_bf16_f32 v73, v78, v79
	v_cvt_pk_bf16_f32 v74, v82, v83
	v_cvt_pk_bf16_f32 v75, v80, v81
	global_store_dwordx4 v[84:85], v[72:75], off
	s_nop 1
	v_mul_f32_e32 v72, v77, v77
	v_mul_f32_e32 v73, v79, v79
	v_fmac_f32_e32 v72, v76, v76
	v_fmac_f32_e32 v73, v78, v78
	v_add_f32_e32 v72, v72, v73
	v_mul_f32_e32 v73, v83, v83
	v_mul_f32_e32 v74, v81, v81
	v_fmac_f32_e32 v73, v82, v82
	v_fmac_f32_e32 v74, v80, v80
	v_add_f32_e32 v73, v73, v74
	v_add_f32_e32 v80, v72, v73
	v_lshlrev_b32_e32 v72, 16, v160
	v_and_b32_e32 v73, 0xffff0000, v160
	v_lshlrev_b32_e32 v74, 16, v161
	v_and_b32_e32 v75, 0xffff0000, v161
	v_lshlrev_b32_e32 v76, 16, v162
	v_and_b32_e32 v77, 0xffff0000, v162
	v_lshlrev_b32_e32 v78, 16, v163
	v_and_b32_e32 v79, 0xffff0000, v163
	v_pk_add_f32 v[68:69], v[68:69], v[72:73]
	v_pk_add_f32 v[70:71], v[70:71], v[74:75]
	v_pk_add_f32 v[72:73], v[66:67], v[78:79]
	v_pk_add_f32 v[66:67], v[64:65], v[76:77]
	v_mul_f32_e32 v65, v69, v69
	v_cvt_pk_bf16_f32 v64, v68, v69
	v_fmac_f32_e32 v65, v68, v68
	v_mul_f32_e32 v68, v71, v71
	v_fmac_f32_e32 v68, v70, v70
	v_add_f32_e32 v65, v65, v68
	v_mul_f32_e32 v68, v67, v67
	v_mul_f32_e32 v69, v73, v73
	v_fmac_f32_e32 v68, v66, v66
	v_fmac_f32_e32 v69, v72, v72
	v_add_f32_e32 v68, v68, v69
	v_add_f32_e32 v65, v65, v68
	v_add_f32_e32 v68, v80, v65
	v_mov_b32_e32 v69, v68
	v_cvt_pk_bf16_f32 v65, v70, v71
	v_cvt_pk_bf16_f32 v66, v66, v67
	v_cvt_pk_bf16_f32 v67, v72, v73
	global_store_dwordx4 v[84:85], v[64:67], off offset:256
	s_waitcnt lgkmcnt(0)
	s_nop 0
	s_nop 1
	v_permlane16_swap_b32_e32 v68, v69
	v_add_f32_e32 v64, v68, v69
	v_mov_b32_e32 v65, v64
	s_nop 1
	v_permlane32_swap_b32_e32 v64, v65
	s_and_saveexec_b64 s[30:31], vcc
	s_cbranch_execz .LBB0_1157
	v_lshl_add_u64 v[66:67], v[214:215], 2, s[14:15]
	v_add_f32_e32 v64, v64, v65
	global_atomic_add_f32 v[66:67], v64, off
.LBB0_1157:
	s_or_b64 exec, exec, s[30:31]
	v_lshlrev_b32_e32 v64, 16, v156
	v_and_b32_e32 v65, 0xffff0000, v156
	v_lshlrev_b32_e32 v66, 16, v157
	v_and_b32_e32 v67, 0xffff0000, v157
	v_lshlrev_b32_e32 v68, 16, v158
	v_and_b32_e32 v69, 0xffff0000, v158
	v_lshlrev_b32_e32 v70, 16, v159
	v_and_b32_e32 v71, 0xffff0000, v159
	v_pk_add_f32 v[62:63], v[62:63], v[66:67]
	v_pk_add_f32 v[60:61], v[60:61], v[64:65]
	v_pk_add_f32 v[64:65], v[58:59], v[70:71]
	v_pk_add_f32 v[66:67], v[56:57], v[68:69]
	v_lshl_add_u64 v[56:57], s[12:13], 0, v[216:217]
	v_lshl_add_u64 v[68:69], v[112:113], 1, v[56:57]
	v_cvt_pk_bf16_f32 v56, v60, v61
	v_cvt_pk_bf16_f32 v57, v62, v63
	v_cvt_pk_bf16_f32 v58, v66, v67
	v_cvt_pk_bf16_f32 v59, v64, v65
	global_store_dwordx4 v[68:69], v[56:59], off
	s_nop 1
	v_mul_f32_e32 v56, v61, v61
	v_mul_f32_e32 v57, v63, v63
	v_fmac_f32_e32 v56, v60, v60
	v_fmac_f32_e32 v57, v62, v62
	v_add_f32_e32 v56, v56, v57
	v_mul_f32_e32 v57, v67, v67
	v_mul_f32_e32 v58, v65, v65
	v_fmac_f32_e32 v57, v66, v66
	v_fmac_f32_e32 v58, v64, v64
	v_add_f32_e32 v57, v57, v58
	v_add_f32_e32 v64, v56, v57
	v_lshlrev_b32_e32 v56, 16, v152
	v_and_b32_e32 v57, 0xffff0000, v152
	v_lshlrev_b32_e32 v58, 16, v153
	v_and_b32_e32 v59, 0xffff0000, v153
	v_lshlrev_b32_e32 v60, 16, v154
	v_and_b32_e32 v61, 0xffff0000, v154
	v_lshlrev_b32_e32 v62, 16, v155
	v_and_b32_e32 v63, 0xffff0000, v155
	v_pk_add_f32 v[52:53], v[52:53], v[56:57]
	v_pk_add_f32 v[54:55], v[54:55], v[58:59]
	v_pk_add_f32 v[56:57], v[50:51], v[62:63]
	v_pk_add_f32 v[50:51], v[48:49], v[60:61]
	v_mul_f32_e32 v49, v53, v53
	v_cvt_pk_bf16_f32 v48, v52, v53
	v_fmac_f32_e32 v49, v52, v52
	v_mul_f32_e32 v52, v55, v55
	v_fmac_f32_e32 v52, v54, v54
	v_add_f32_e32 v49, v49, v52
	v_mul_f32_e32 v52, v51, v51
	v_mul_f32_e32 v53, v57, v57
	v_fmac_f32_e32 v52, v50, v50
	v_fmac_f32_e32 v53, v56, v56
	v_add_f32_e32 v52, v52, v53
	v_add_f32_e32 v49, v49, v52
	v_add_f32_e32 v52, v64, v49
	v_mov_b32_e32 v53, v52
	v_cvt_pk_bf16_f32 v49, v54, v55
	v_cvt_pk_bf16_f32 v50, v50, v51
	v_cvt_pk_bf16_f32 v51, v56, v57
	global_store_dwordx4 v[68:69], v[48:51], off offset:256
	s_waitcnt lgkmcnt(0)
	s_nop 0
	s_nop 1
	v_permlane16_swap_b32_e32 v52, v53
	v_add_f32_e32 v48, v52, v53
	v_mov_b32_e32 v49, v48
	s_nop 1
	v_permlane32_swap_b32_e32 v48, v49
	s_and_saveexec_b64 s[30:31], vcc
	s_cbranch_execz .LBB0_1159
	v_lshl_add_u64 v[50:51], v[210:211], 2, s[14:15]
	v_add_f32_e32 v48, v48, v49
	global_atomic_add_f32 v[50:51], v48, off
.LBB0_1159:
	s_or_b64 exec, exec, s[30:31]
	v_lshlrev_b32_e32 v48, 16, v148
	v_and_b32_e32 v49, 0xffff0000, v148
	v_lshlrev_b32_e32 v50, 16, v149
	v_and_b32_e32 v51, 0xffff0000, v149
	v_lshlrev_b32_e32 v52, 16, v150
	v_and_b32_e32 v53, 0xffff0000, v150
	v_lshlrev_b32_e32 v54, 16, v151
	v_and_b32_e32 v55, 0xffff0000, v151
	v_pk_add_f32 v[46:47], v[46:47], v[50:51]
	v_pk_add_f32 v[44:45], v[44:45], v[48:49]
	v_pk_add_f32 v[48:49], v[42:43], v[54:55]
	v_pk_add_f32 v[50:51], v[40:41], v[52:53]
	v_lshl_add_u64 v[40:41], s[12:13], 0, v[212:213]
	v_lshl_add_u64 v[52:53], v[112:113], 1, v[40:41]
	v_cvt_pk_bf16_f32 v40, v44, v45
	v_cvt_pk_bf16_f32 v41, v46, v47
	v_cvt_pk_bf16_f32 v42, v50, v51
	v_cvt_pk_bf16_f32 v43, v48, v49
	global_store_dwordx4 v[52:53], v[40:43], off
	s_nop 1
	v_mul_f32_e32 v40, v45, v45
	v_mul_f32_e32 v41, v47, v47
	v_fmac_f32_e32 v40, v44, v44
	v_fmac_f32_e32 v41, v46, v46
	v_add_f32_e32 v40, v40, v41
	v_mul_f32_e32 v41, v51, v51
	v_mul_f32_e32 v42, v49, v49
	v_fmac_f32_e32 v41, v50, v50
	v_fmac_f32_e32 v42, v48, v48
	v_add_f32_e32 v41, v41, v42
	v_add_f32_e32 v48, v40, v41
	v_lshlrev_b32_e32 v40, 16, v144
	v_and_b32_e32 v41, 0xffff0000, v144
	v_lshlrev_b32_e32 v42, 16, v145
	v_and_b32_e32 v43, 0xffff0000, v145
	v_lshlrev_b32_e32 v44, 16, v146
	v_and_b32_e32 v45, 0xffff0000, v146
	v_lshlrev_b32_e32 v46, 16, v147
	v_and_b32_e32 v47, 0xffff0000, v147
	v_pk_add_f32 v[36:37], v[36:37], v[40:41]
	v_pk_add_f32 v[38:39], v[38:39], v[42:43]
	v_pk_add_f32 v[40:41], v[34:35], v[46:47]
	v_pk_add_f32 v[34:35], v[32:33], v[44:45]
	v_mul_f32_e32 v33, v37, v37
	v_cvt_pk_bf16_f32 v32, v36, v37
	v_fmac_f32_e32 v33, v36, v36
	v_mul_f32_e32 v36, v39, v39
	v_fmac_f32_e32 v36, v38, v38
	v_add_f32_e32 v33, v33, v36
	v_mul_f32_e32 v36, v35, v35
	v_mul_f32_e32 v37, v41, v41
	v_fmac_f32_e32 v36, v34, v34
	v_fmac_f32_e32 v37, v40, v40
	v_add_f32_e32 v36, v36, v37
	v_add_f32_e32 v33, v33, v36
	v_add_f32_e32 v36, v48, v33
	v_mov_b32_e32 v37, v36
	v_cvt_pk_bf16_f32 v33, v38, v39
	v_cvt_pk_bf16_f32 v34, v34, v35
	v_cvt_pk_bf16_f32 v35, v40, v41
	global_store_dwordx4 v[52:53], v[32:35], off offset:256
	s_waitcnt lgkmcnt(0)
	s_nop 0
	s_nop 1
	v_permlane16_swap_b32_e32 v36, v37
	v_add_f32_e32 v32, v36, v37
	v_mov_b32_e32 v33, v32
	s_nop 1
	v_permlane32_swap_b32_e32 v32, v33
	s_and_saveexec_b64 s[30:31], vcc
	s_cbranch_execz .LBB0_1161
	v_lshl_add_u64 v[34:35], v[208:209], 2, s[14:15]
	v_add_f32_e32 v32, v32, v33
	global_atomic_add_f32 v[34:35], v32, off
.LBB0_1161:
	s_or_b64 exec, exec, s[30:31]
	v_lshlrev_b32_e32 v32, 16, v140
	v_and_b32_e32 v33, 0xffff0000, v140
	v_lshlrev_b32_e32 v34, 16, v141
	v_and_b32_e32 v35, 0xffff0000, v141
	v_lshlrev_b32_e32 v36, 16, v142
	v_and_b32_e32 v37, 0xffff0000, v142
	v_lshlrev_b32_e32 v38, 16, v143
	v_and_b32_e32 v39, 0xffff0000, v143
	v_pk_add_f32 v[30:31], v[30:31], v[34:35]
	v_pk_add_f32 v[28:29], v[28:29], v[32:33]
	v_pk_add_f32 v[32:33], v[26:27], v[38:39]
	v_pk_add_f32 v[34:35], v[24:25], v[36:37]
	v_lshl_add_u64 v[24:25], s[12:13], 0, v[206:207]
	v_lshl_add_u64 v[36:37], v[112:113], 1, v[24:25]
	v_cvt_pk_bf16_f32 v24, v28, v29
	v_cvt_pk_bf16_f32 v25, v30, v31
	v_cvt_pk_bf16_f32 v26, v34, v35
	v_cvt_pk_bf16_f32 v27, v32, v33
	global_store_dwordx4 v[36:37], v[24:27], off
	s_nop 1
	v_mul_f32_e32 v24, v29, v29
	v_mul_f32_e32 v25, v31, v31
	v_fmac_f32_e32 v24, v28, v28
	v_fmac_f32_e32 v25, v30, v30
	v_add_f32_e32 v24, v24, v25
	v_mul_f32_e32 v25, v35, v35
	v_mul_f32_e32 v26, v33, v33
	v_fmac_f32_e32 v25, v34, v34
	v_fmac_f32_e32 v26, v32, v32
	v_add_f32_e32 v25, v25, v26
	v_add_f32_e32 v32, v24, v25
	v_lshlrev_b32_e32 v24, 16, v136
	v_and_b32_e32 v25, 0xffff0000, v136
	v_lshlrev_b32_e32 v26, 16, v137
	v_and_b32_e32 v27, 0xffff0000, v137
	v_lshlrev_b32_e32 v28, 16, v138
	v_and_b32_e32 v29, 0xffff0000, v138
	v_lshlrev_b32_e32 v30, 16, v139
	v_and_b32_e32 v31, 0xffff0000, v139
	v_pk_add_f32 v[20:21], v[20:21], v[24:25]
	v_pk_add_f32 v[22:23], v[22:23], v[26:27]
	v_pk_add_f32 v[24:25], v[18:19], v[30:31]
	v_pk_add_f32 v[18:19], v[16:17], v[28:29]
	v_mul_f32_e32 v17, v21, v21
	v_cvt_pk_bf16_f32 v16, v20, v21
	v_fmac_f32_e32 v17, v20, v20
	v_mul_f32_e32 v20, v23, v23
	v_fmac_f32_e32 v20, v22, v22
	v_add_f32_e32 v17, v17, v20
	v_mul_f32_e32 v20, v19, v19
	v_mul_f32_e32 v21, v25, v25
	v_fmac_f32_e32 v20, v18, v18
	v_fmac_f32_e32 v21, v24, v24
	v_add_f32_e32 v20, v20, v21
	v_add_f32_e32 v17, v17, v20
	v_add_f32_e32 v20, v32, v17
	v_mov_b32_e32 v21, v20
	v_cvt_pk_bf16_f32 v17, v22, v23
	v_cvt_pk_bf16_f32 v18, v18, v19
	v_cvt_pk_bf16_f32 v19, v24, v25
	global_store_dwordx4 v[36:37], v[16:19], off offset:256
	s_waitcnt lgkmcnt(0)
	s_nop 0
	s_nop 1
	v_permlane16_swap_b32_e32 v20, v21
	v_add_f32_e32 v16, v20, v21
	v_mov_b32_e32 v17, v16
	s_nop 1
	v_permlane32_swap_b32_e32 v16, v17
	s_and_saveexec_b64 s[30:31], vcc
	s_cbranch_execz .LBB0_1163
	v_lshl_add_u64 v[18:19], v[204:205], 2, s[14:15]
	v_add_f32_e32 v16, v16, v17
	global_atomic_add_f32 v[18:19], v16, off
.LBB0_1163:
	s_or_b64 exec, exec, s[30:31]
	v_lshlrev_b32_e32 v16, 16, v132
	v_and_b32_e32 v17, 0xffff0000, v132
	v_lshlrev_b32_e32 v18, 16, v133
	v_and_b32_e32 v19, 0xffff0000, v133
	v_lshlrev_b32_e32 v20, 16, v134
	v_and_b32_e32 v21, 0xffff0000, v134
	v_lshlrev_b32_e32 v22, 16, v135
	v_and_b32_e32 v23, 0xffff0000, v135
	v_pk_add_f32 v[14:15], v[14:15], v[18:19]
	v_pk_add_f32 v[12:13], v[12:13], v[16:17]
	v_pk_add_f32 v[16:17], v[10:11], v[22:23]
	v_pk_add_f32 v[18:19], v[8:9], v[20:21]
	v_lshl_add_u64 v[8:9], s[12:13], 0, v[202:203]
	v_lshl_add_u64 v[20:21], v[112:113], 1, v[8:9]
	v_cvt_pk_bf16_f32 v8, v12, v13
	v_cvt_pk_bf16_f32 v9, v14, v15
	v_cvt_pk_bf16_f32 v10, v18, v19
	v_cvt_pk_bf16_f32 v11, v16, v17
	global_store_dwordx4 v[20:21], v[8:11], off
	s_nop 1
	v_mul_f32_e32 v8, v13, v13
	v_mul_f32_e32 v9, v15, v15
	v_fmac_f32_e32 v8, v12, v12
	v_fmac_f32_e32 v9, v14, v14
	v_add_f32_e32 v8, v8, v9
	v_mul_f32_e32 v9, v19, v19
	v_mul_f32_e32 v10, v17, v17
	v_fmac_f32_e32 v9, v18, v18
	v_fmac_f32_e32 v10, v16, v16
	v_add_f32_e32 v9, v9, v10
	v_add_f32_e32 v16, v8, v9
	v_lshlrev_b32_e32 v8, 16, v120
	v_and_b32_e32 v9, 0xffff0000, v120
	v_lshlrev_b32_e32 v10, 16, v121
	v_and_b32_e32 v11, 0xffff0000, v121
	v_lshlrev_b32_e32 v12, 16, v122
	v_and_b32_e32 v13, 0xffff0000, v122
	v_lshlrev_b32_e32 v14, 16, v123
	v_and_b32_e32 v15, 0xffff0000, v123
	v_pk_add_f32 v[4:5], v[4:5], v[8:9]
	v_pk_add_f32 v[6:7], v[6:7], v[10:11]
	v_pk_add_f32 v[8:9], v[2:3], v[14:15]
	v_pk_add_f32 v[2:3], v[0:1], v[12:13]
	v_mul_f32_e32 v1, v5, v5
	v_cvt_pk_bf16_f32 v0, v4, v5
	v_fmac_f32_e32 v1, v4, v4
	v_mul_f32_e32 v4, v7, v7
	v_fmac_f32_e32 v4, v6, v6
	v_add_f32_e32 v1, v1, v4
	v_mul_f32_e32 v4, v3, v3
	v_mul_f32_e32 v5, v9, v9
	v_fmac_f32_e32 v4, v2, v2
	v_fmac_f32_e32 v5, v8, v8
	v_add_f32_e32 v4, v4, v5
	v_add_f32_e32 v1, v1, v4
	v_add_f32_e32 v4, v16, v1
	v_mov_b32_e32 v5, v4
	v_cvt_pk_bf16_f32 v1, v6, v7
	v_cvt_pk_bf16_f32 v2, v2, v3
	v_cvt_pk_bf16_f32 v3, v8, v9
	global_store_dwordx4 v[20:21], v[0:3], off offset:256
	s_waitcnt lgkmcnt(0)
	s_nop 0
	s_nop 1
	v_permlane16_swap_b32_e32 v4, v5
	v_add_f32_e32 v0, v4, v5
	v_mov_b32_e32 v1, v0
	s_nop 1
	v_permlane32_swap_b32_e32 v0, v1
	s_and_saveexec_b64 s[30:31], vcc
	s_cbranch_execz .LBB0_1165
	v_lshl_add_u64 v[2:3], v[200:201], 2, s[14:15]
	v_add_f32_e32 v0, v0, v1
	global_atomic_add_f32 v[2:3], v0, off
